# k28: k27 + first-half residual rows touched with throw-away loads at the unit-loop header (before the K loop) in the 6 residual-epilogue phases
# baseline (speedup 1.0000x reference)
.LBB0_573:
	v_lshl_add_u32 v238, s13, 8, v182
	v_lshlrev_b32_e32 v238, 11, v238
	v_mov_b32_e32 v239, 0
	v_lshl_or_b32 v240, s12, 8, v184
	v_lshlrev_b32_e32 v240, 1, v240
	v_mov_b32_e32 v241, 0
	v_lshl_add_u64 v[240:241], s[78:79], 0, v[240:241]
	v_lshl_add_u64 v[238:239], v[240:241], 0, v[238:239]
	v_mov_b32_e32 v242, 0x8000
	v_mov_b32_e32 v243, 0
	global_load_dwordx4 v[246:249], v[238:239], off
	global_load_dwordx4 v[246:249], v[238:239], off offset:256
	v_lshl_add_u64 v[238:239], v[238:239], 0, v[242:243]
	global_load_dwordx4 v[246:249], v[238:239], off
	global_load_dwordx4 v[246:249], v[238:239], off offset:256
	v_lshl_add_u64 v[238:239], v[238:239], 0, v[242:243]
	global_load_dwordx4 v[246:249], v[238:239], off
	global_load_dwordx4 v[246:249], v[238:239], off offset:256
	v_lshl_add_u64 v[238:239], v[238:239], 0, v[242:243]
	global_load_dwordx4 v[246:249], v[238:239], off
	global_load_dwordx4 v[246:249], v[238:239], off offset:256
	s_add_i32 s36, s36, 1
	s_mul_i32 s0, s36, s39
	s_mul_hi_u32 s1, s36, s75
	s_add_i32 s1, s1, s0
	s_mul_i32 s0, s36, s75
	s_add_u32 s6, s0, s64
	s_addc_u32 s7, s1, s40
	v_cmp_gt_i64_e32 vcc, s[6:7], v[168:169]
	v_cmp_lt_i64_e64 s[8:9], s[6:7], v[166:167]
	s_cbranch_vccnz .LBB0_579
	s_ashr_i32 s0, s6, 31
	s_lshr_b32 s0, s0, 29
	s_add_i32 s0, s6, s0
	s_and_b32 s1, s0, -8
	s_sub_i32 s1, s6, s1
	s_cmp_gt_i32 s1, -1
	s_mov_b64 s[6:7], -1
	s_cbranch_scc0 .LBB0_576
	s_lshl_b32 s20, s1, 5
	s_mov_b64 s[6:7], 0

.LBB0_583:
	s_add_u32 s22, s22, 0xb0080
	s_addc_u32 s23, s23, 0
	s_add_u32 s45, s2, 0x100
	v_mov_b32_e32 v2, 0
	s_addc_u32 s46, s3, 0
	s_mov_b32 s47, -2
	s_waitcnt lgkmcnt(0)
	v_mov_b32_e32 v3, v2
	v_mov_b32_e32 v4, v2
	v_mov_b32_e32 v5, v2
	v_mov_b32_e32 v6, v2
	v_mov_b32_e32 v7, v2
	v_mov_b32_e32 v8, v2
	v_mov_b32_e32 v9, v2
	v_mov_b32_e32 v18, v2
	v_mov_b32_e32 v19, v2
	v_mov_b32_e32 v20, v2
	v_mov_b32_e32 v21, v2
	v_mov_b32_e32 v22, v2
	v_mov_b32_e32 v23, v2
	v_mov_b32_e32 v24, v2
	v_mov_b32_e32 v25, v2
	v_mov_b32_e32 v34, v2
	v_mov_b32_e32 v35, v2
	v_mov_b32_e32 v36, v2
	v_mov_b32_e32 v37, v2
	v_mov_b32_e32 v38, v2
	v_mov_b32_e32 v39, v2
	v_mov_b32_e32 v40, v2
	v_mov_b32_e32 v41, v2
	v_mov_b32_e32 v50, v2
	v_mov_b32_e32 v51, v2
	v_mov_b32_e32 v52, v2
	v_mov_b32_e32 v53, v2
	v_mov_b32_e32 v54, v2
	v_mov_b32_e32 v55, v2
	v_mov_b32_e32 v56, v2
	v_mov_b32_e32 v57, v2
	v_mov_b32_e32 v10, v2
	v_mov_b32_e32 v11, v2
	v_mov_b32_e32 v12, v2
	v_mov_b32_e32 v13, v2
	v_mov_b32_e32 v14, v2
	v_mov_b32_e32 v15, v2
	v_mov_b32_e32 v16, v2
	v_mov_b32_e32 v17, v2
	v_mov_b32_e32 v26, v2
	v_mov_b32_e32 v27, v2
	v_mov_b32_e32 v28, v2
	v_mov_b32_e32 v29, v2
	v_mov_b32_e32 v30, v2
	v_mov_b32_e32 v31, v2
	v_mov_b32_e32 v32, v2
	v_mov_b32_e32 v33, v2
	v_mov_b32_e32 v42, v2
	v_mov_b32_e32 v43, v2
	v_mov_b32_e32 v44, v2
	v_mov_b32_e32 v45, v2
	v_mov_b32_e32 v46, v2
	v_mov_b32_e32 v47, v2
	v_mov_b32_e32 v48, v2
	v_mov_b32_e32 v49, v2
	v_mov_b32_e32 v58, v2
	v_mov_b32_e32 v59, v2
	v_mov_b32_e32 v60, v2
	v_mov_b32_e32 v61, v2
	v_mov_b32_e32 v62, v2
	v_mov_b32_e32 v63, v2
	v_mov_b32_e32 v64, v2
	v_mov_b32_e32 v65, v2
	v_mov_b32_e32 v66, v2
	v_mov_b32_e32 v67, v2
	v_mov_b32_e32 v68, v2
	v_mov_b32_e32 v69, v2
	v_mov_b32_e32 v70, v2
	v_mov_b32_e32 v71, v2
	v_mov_b32_e32 v72, v2
	v_mov_b32_e32 v73, v2
	v_mov_b32_e32 v82, v2
	v_mov_b32_e32 v83, v2
	v_mov_b32_e32 v84, v2
	v_mov_b32_e32 v85, v2
	v_mov_b32_e32 v86, v2
	v_mov_b32_e32 v87, v2
	v_mov_b32_e32 v88, v2
	v_mov_b32_e32 v89, v2
	v_mov_b32_e32 v98, v2
	v_mov_b32_e32 v99, v2
	v_mov_b32_e32 v100, v2
	v_mov_b32_e32 v101, v2
	v_mov_b32_e32 v102, v2
	v_mov_b32_e32 v103, v2
	v_mov_b32_e32 v104, v2
	v_mov_b32_e32 v105, v2
	v_mov_b32_e32 v114, v2
	v_mov_b32_e32 v115, v2
	v_mov_b32_e32 v116, v2
	v_mov_b32_e32 v117, v2
	v_mov_b32_e32 v118, v2
	v_mov_b32_e32 v119, v2
	v_mov_b32_e32 v120, v2
	v_mov_b32_e32 v121, v2
	v_mov_b32_e32 v74, v2
	v_mov_b32_e32 v75, v2
	v_mov_b32_e32 v76, v2
	v_mov_b32_e32 v77, v2
	v_mov_b32_e32 v78, v2
	v_mov_b32_e32 v79, v2
	v_mov_b32_e32 v80, v2
	v_mov_b32_e32 v81, v2
	v_mov_b32_e32 v90, v2
	v_mov_b32_e32 v91, v2
	v_mov_b32_e32 v92, v2
	v_mov_b32_e32 v93, v2
	v_mov_b32_e32 v94, v2
	v_mov_b32_e32 v95, v2
	v_mov_b32_e32 v96, v2
	v_mov_b32_e32 v97, v2
	v_mov_b32_e32 v106, v2
	v_mov_b32_e32 v107, v2
	v_mov_b32_e32 v108, v2
	v_mov_b32_e32 v109, v2
	v_mov_b32_e32 v110, v2
	v_mov_b32_e32 v111, v2
	v_mov_b32_e32 v112, v2
	v_mov_b32_e32 v113, v2
	v_mov_b32_e32 v122, v2
	v_mov_b32_e32 v123, v2
	v_mov_b32_e32 v124, v2
	v_mov_b32_e32 v125, v2
	v_mov_b32_e32 v126, v2
	v_mov_b32_e32 v127, v2
	v_mov_b32_e32 v128, v2
	v_mov_b32_e32 v129, v2
	s_nop 0
	s_nop 0
	s_nop 0
	s_nop 0
	s_nop 0
.LBB0_584:
	ds_read_b128 v[130:133], v187
	ds_read_b128 v[134:137], v187 offset:1024
	ds_read_b128 v[138:141], v187 offset:2048
	ds_read_b128 v[142:145], v187 offset:3072
	ds_read_b128 v[146:149], v188
	ds_read_b128 v[150:153], v188 offset:1024
	ds_read_b128 v[170:173], v188 offset:2048
	ds_read_b128 v[174:177], v188 offset:3072
	s_add_u32 s0, s22, 0xfff50080
	s_addc_u32 s1, s23, -1
	s_cmp_eq_u32 s47, 40
	s_cselect_b32 s25, s9, s1
	s_cselect_b32 s24, s8, s0
	s_cselect_b32 s3, s21, s46
	s_cselect_b32 s2, s20, s45
	v_lshl_add_u64 v[220:221], s[22:23], 0, v[162:163]
	s_add_i32 m0, s31, 0xc000
	ds_read_b128 v[178:181], v189
	ds_read_b128 v[192:195], v189 offset:1024
	ds_read_b128 v[196:199], v189 offset:2048
	ds_read_b128 v[200:203], v189 offset:3072
	ds_read_b128 v[204:207], v189 offset:4096
	ds_read_b128 v[208:211], v189 offset:5120
	ds_read_b128 v[212:215], v189 offset:6144
	ds_read_b128 v[216:219], v189 offset:7168
	global_load_lds_dwordx4 v[220:221], off
	v_lshl_add_u64 v[220:221], s[22:23], 0, v[164:165]
	s_add_i32 m0, s31, 0xe000
	s_nop 0
	global_load_lds_dwordx4 v[220:221], off
	s_waitcnt vmcnt(8)
	s_waitcnt lgkmcnt(0)
	s_barrier
	s_setprio 1
	s_waitcnt lgkmcnt(0)
	v_mfma_f32_16x16x32_bf16 v[126:129], v[130:133], v[178:181], v[126:129]
	v_mfma_f32_16x16x32_bf16 v[126:129], v[134:137], v[192:195], v[126:129]
	v_mfma_f32_16x16x32_bf16 v[122:125], v[138:141], v[178:181], v[122:125]
	v_mfma_f32_16x16x32_bf16 v[122:125], v[142:145], v[192:195], v[122:125]
	v_mfma_f32_16x16x32_bf16 v[110:113], v[130:133], v[196:199], v[110:113]
	v_mfma_f32_16x16x32_bf16 v[110:113], v[134:137], v[200:203], v[110:113]
	v_mfma_f32_16x16x32_bf16 v[106:109], v[138:141], v[196:199], v[106:109]
	v_mfma_f32_16x16x32_bf16 v[106:109], v[142:145], v[200:203], v[106:109]
	v_mfma_f32_16x16x32_bf16 v[94:97], v[130:133], v[204:207], v[94:97]
	v_mfma_f32_16x16x32_bf16 v[94:97], v[134:137], v[208:211], v[94:97]
	v_mfma_f32_16x16x32_bf16 v[90:93], v[138:141], v[204:207], v[90:93]
	v_mfma_f32_16x16x32_bf16 v[90:93], v[142:145], v[208:211], v[90:93]
	v_mfma_f32_16x16x32_bf16 v[78:81], v[130:133], v[212:215], v[78:81]
	v_mfma_f32_16x16x32_bf16 v[78:81], v[134:137], v[216:219], v[78:81]
	v_mfma_f32_16x16x32_bf16 v[74:77], v[138:141], v[212:215], v[74:77]
	v_mfma_f32_16x16x32_bf16 v[74:77], v[142:145], v[216:219], v[74:77]
	s_setprio 0
	s_setprio 1
	v_mfma_f32_16x16x32_bf16 v[118:121], v[146:149], v[178:181], v[118:121]
	v_mfma_f32_16x16x32_bf16 v[118:121], v[150:153], v[192:195], v[118:121]
	v_mfma_f32_16x16x32_bf16 v[114:117], v[170:173], v[178:181], v[114:117]
	v_mfma_f32_16x16x32_bf16 v[114:117], v[174:177], v[192:195], v[114:117]
	v_mfma_f32_16x16x32_bf16 v[102:105], v[146:149], v[196:199], v[102:105]
	v_mfma_f32_16x16x32_bf16 v[102:105], v[150:153], v[200:203], v[102:105]
	v_mfma_f32_16x16x32_bf16 v[98:101], v[170:173], v[196:199], v[98:101]
	v_mfma_f32_16x16x32_bf16 v[98:101], v[174:177], v[200:203], v[98:101]
	v_mfma_f32_16x16x32_bf16 v[86:89], v[146:149], v[204:207], v[86:89]
	v_mfma_f32_16x16x32_bf16 v[86:89], v[150:153], v[208:211], v[86:89]
	v_mfma_f32_16x16x32_bf16 v[82:85], v[170:173], v[204:207], v[82:85]
	v_mfma_f32_16x16x32_bf16 v[82:85], v[174:177], v[208:211], v[82:85]
	v_mfma_f32_16x16x32_bf16 v[70:73], v[146:149], v[212:215], v[70:73]
	v_mfma_f32_16x16x32_bf16 v[70:73], v[150:153], v[216:219], v[70:73]
	v_mfma_f32_16x16x32_bf16 v[66:69], v[170:173], v[212:215], v[66:69]
	v_mfma_f32_16x16x32_bf16 v[66:69], v[174:177], v[216:219], v[66:69]
	s_setprio 0
	s_barrier
	s_add_i32 s0, s41, s30
	v_lshl_add_u64 v[220:221], s[2:3], 0, v[156:157]
	s_mov_b32 m0, s0
	ds_read_b128 v[178:181], v189 offset:16384
	ds_read_b128 v[192:195], v189 offset:17408
	ds_read_b128 v[196:199], v189 offset:18432
	ds_read_b128 v[200:203], v189 offset:19456
	ds_read_b128 v[204:207], v189 offset:20480
	ds_read_b128 v[208:211], v189 offset:21504
	ds_read_b128 v[212:215], v189 offset:22528
	ds_read_b128 v[216:219], v189 offset:23552
	global_load_lds_dwordx4 v[220:221], off
	s_add_i32 m0, s0, 0x2000
	s_add_u32 s0, s2, 0xb0000
	v_lshl_add_u64 v[222:223], s[2:3], 0, v[160:161]
	s_addc_u32 s1, s3, 0
	s_add_i32 s48, s42, s30
	global_load_lds_dwordx4 v[222:223], off
	v_lshl_add_u64 v[224:225], s[0:1], 0, v[156:157]
	s_mov_b32 m0, s48
	v_lshl_add_u64 v[226:227], s[24:25], 0, v[158:159]
	global_load_lds_dwordx4 v[224:225], off
	v_lshl_add_u64 v[224:225], s[0:1], 0, v[160:161]
	s_add_i32 m0, s48, 0x2000
	s_nop 0
	global_load_lds_dwordx4 v[224:225], off
	v_lshl_add_u64 v[224:225], s[24:25], 0, v[154:155]
	s_mov_b32 m0, s31
	s_nop 0
	global_load_lds_dwordx4 v[224:225], off
	s_mov_b32 m0, s33
	s_nop 0
	global_load_lds_dwordx4 v[226:227], off
	s_waitcnt vmcnt(8)
	s_waitcnt lgkmcnt(0)
	s_barrier
	s_setprio 1
	s_waitcnt lgkmcnt(0)
	v_mfma_f32_16x16x32_bf16 v[62:65], v[130:133], v[178:181], v[62:65]
	v_mfma_f32_16x16x32_bf16 v[62:65], v[134:137], v[192:195], v[62:65]
	v_mfma_f32_16x16x32_bf16 v[58:61], v[138:141], v[178:181], v[58:61]
	v_mfma_f32_16x16x32_bf16 v[58:61], v[142:145], v[192:195], v[58:61]
	v_mfma_f32_16x16x32_bf16 v[46:49], v[130:133], v[196:199], v[46:49]
	v_mfma_f32_16x16x32_bf16 v[46:49], v[134:137], v[200:203], v[46:49]
	v_mfma_f32_16x16x32_bf16 v[42:45], v[138:141], v[196:199], v[42:45]
	v_mfma_f32_16x16x32_bf16 v[42:45], v[142:145], v[200:203], v[42:45]
	v_mfma_f32_16x16x32_bf16 v[30:33], v[130:133], v[204:207], v[30:33]
	v_mfma_f32_16x16x32_bf16 v[30:33], v[134:137], v[208:211], v[30:33]
	v_mfma_f32_16x16x32_bf16 v[26:29], v[138:141], v[204:207], v[26:29]
	v_mfma_f32_16x16x32_bf16 v[26:29], v[142:145], v[208:211], v[26:29]
	v_mfma_f32_16x16x32_bf16 v[14:17], v[130:133], v[212:215], v[14:17]
	v_mfma_f32_16x16x32_bf16 v[14:17], v[134:137], v[216:219], v[14:17]
	v_mfma_f32_16x16x32_bf16 v[10:13], v[138:141], v[212:215], v[10:13]
	v_mfma_f32_16x16x32_bf16 v[10:13], v[142:145], v[216:219], v[10:13]
	s_setprio 0
	s_setprio 1
	v_mfma_f32_16x16x32_bf16 v[54:57], v[146:149], v[178:181], v[54:57]
	v_mfma_f32_16x16x32_bf16 v[54:57], v[150:153], v[192:195], v[54:57]
	v_mfma_f32_16x16x32_bf16 v[50:53], v[170:173], v[178:181], v[50:53]
	v_mfma_f32_16x16x32_bf16 v[50:53], v[174:177], v[192:195], v[50:53]
	v_mfma_f32_16x16x32_bf16 v[38:41], v[146:149], v[196:199], v[38:41]
	v_mfma_f32_16x16x32_bf16 v[38:41], v[150:153], v[200:203], v[38:41]
	v_mfma_f32_16x16x32_bf16 v[34:37], v[170:173], v[196:199], v[34:37]
	v_mfma_f32_16x16x32_bf16 v[34:37], v[174:177], v[200:203], v[34:37]
	v_mfma_f32_16x16x32_bf16 v[22:25], v[146:149], v[204:207], v[22:25]
	v_mfma_f32_16x16x32_bf16 v[22:25], v[150:153], v[208:211], v[22:25]
	v_mfma_f32_16x16x32_bf16 v[18:21], v[170:173], v[204:207], v[18:21]
	v_mfma_f32_16x16x32_bf16 v[18:21], v[174:177], v[208:211], v[18:21]
	v_mfma_f32_16x16x32_bf16 v[6:9], v[146:149], v[212:215], v[6:9]
	v_mfma_f32_16x16x32_bf16 v[6:9], v[150:153], v[216:219], v[6:9]
	v_mfma_f32_16x16x32_bf16 v[2:5], v[170:173], v[212:215], v[2:5]
	v_mfma_f32_16x16x32_bf16 v[2:5], v[174:177], v[216:219], v[2:5]
	s_setprio 0
	s_barrier
	s_add_i32 s48, 0, 0x18000
	s_add_i32 s49, 0, 0x1c000
	v_add_u32_e32 v142, s48, v183
	v_add_u32_e32 v174, s49, v183
	ds_read_b128 v[130:133], v142
	ds_read_b128 v[134:137], v142 offset:1024
	ds_read_b128 v[138:141], v142 offset:2048
	ds_read_b128 v[142:145], v142 offset:3072
	ds_read_b128 v[146:149], v174
	ds_read_b128 v[150:153], v174 offset:1024
	ds_read_b128 v[170:173], v174 offset:2048
	ds_read_b128 v[174:177], v174 offset:3072
	s_add_u32 s0, s24, 0xb0000
	s_addc_u32 s1, s25, 0
	s_mov_b32 m0, s34
	v_lshl_add_u64 v[228:229], s[0:1], 0, v[154:155]
	ds_read_b128 v[178:181], v189 offset:32768
	ds_read_b128 v[192:195], v189 offset:33792
	ds_read_b128 v[196:199], v189 offset:34816
	ds_read_b128 v[200:203], v189 offset:35840
	ds_read_b128 v[204:207], v189 offset:36864
	ds_read_b128 v[208:211], v189 offset:37888
	ds_read_b128 v[212:215], v189 offset:38912
	ds_read_b128 v[216:219], v189 offset:39936
	global_load_lds_dwordx4 v[228:229], off
	v_lshl_add_u64 v[228:229], s[0:1], 0, v[158:159]
	s_mov_b32 m0, s35
	s_nop 0
	global_load_lds_dwordx4 v[228:229], off
	s_waitcnt vmcnt(8)
	s_waitcnt lgkmcnt(0)
	s_barrier
	s_setprio 1
	s_waitcnt lgkmcnt(0)
	v_mfma_f32_16x16x32_bf16 v[126:129], v[130:133], v[178:181], v[126:129]
	v_mfma_f32_16x16x32_bf16 v[126:129], v[134:137], v[192:195], v[126:129]
	v_mfma_f32_16x16x32_bf16 v[122:125], v[138:141], v[178:181], v[122:125]
	v_mfma_f32_16x16x32_bf16 v[122:125], v[142:145], v[192:195], v[122:125]
	v_mfma_f32_16x16x32_bf16 v[110:113], v[130:133], v[196:199], v[110:113]
	v_mfma_f32_16x16x32_bf16 v[110:113], v[134:137], v[200:203], v[110:113]
	v_mfma_f32_16x16x32_bf16 v[106:109], v[138:141], v[196:199], v[106:109]
	v_mfma_f32_16x16x32_bf16 v[106:109], v[142:145], v[200:203], v[106:109]
	v_mfma_f32_16x16x32_bf16 v[94:97], v[130:133], v[204:207], v[94:97]
	v_mfma_f32_16x16x32_bf16 v[94:97], v[134:137], v[208:211], v[94:97]
	v_mfma_f32_16x16x32_bf16 v[90:93], v[138:141], v[204:207], v[90:93]
	v_mfma_f32_16x16x32_bf16 v[90:93], v[142:145], v[208:211], v[90:93]
	v_mfma_f32_16x16x32_bf16 v[78:81], v[130:133], v[212:215], v[78:81]
	v_mfma_f32_16x16x32_bf16 v[78:81], v[134:137], v[216:219], v[78:81]
	v_mfma_f32_16x16x32_bf16 v[74:77], v[138:141], v[212:215], v[74:77]
	v_mfma_f32_16x16x32_bf16 v[74:77], v[142:145], v[216:219], v[74:77]
	s_setprio 0
	s_setprio 1
	v_mfma_f32_16x16x32_bf16 v[118:121], v[146:149], v[178:181], v[118:121]
	v_mfma_f32_16x16x32_bf16 v[118:121], v[150:153], v[192:195], v[118:121]
	v_mfma_f32_16x16x32_bf16 v[114:117], v[170:173], v[178:181], v[114:117]
	v_mfma_f32_16x16x32_bf16 v[114:117], v[174:177], v[192:195], v[114:117]
	v_mfma_f32_16x16x32_bf16 v[102:105], v[146:149], v[196:199], v[102:105]
	v_mfma_f32_16x16x32_bf16 v[102:105], v[150:153], v[200:203], v[102:105]
	v_mfma_f32_16x16x32_bf16 v[98:101], v[170:173], v[196:199], v[98:101]
	v_mfma_f32_16x16x32_bf16 v[98:101], v[174:177], v[200:203], v[98:101]
	v_mfma_f32_16x16x32_bf16 v[86:89], v[146:149], v[204:207], v[86:89]
	v_mfma_f32_16x16x32_bf16 v[86:89], v[150:153], v[208:211], v[86:89]
	v_mfma_f32_16x16x32_bf16 v[82:85], v[170:173], v[204:207], v[82:85]
	v_mfma_f32_16x16x32_bf16 v[82:85], v[174:177], v[208:211], v[82:85]
	v_mfma_f32_16x16x32_bf16 v[70:73], v[146:149], v[212:215], v[70:73]
	v_mfma_f32_16x16x32_bf16 v[70:73], v[150:153], v[216:219], v[70:73]
	v_mfma_f32_16x16x32_bf16 v[66:69], v[170:173], v[212:215], v[66:69]
	v_mfma_f32_16x16x32_bf16 v[66:69], v[174:177], v[216:219], v[66:69]
	s_setprio 0
	s_barrier
	s_add_i32 s0, s48, s30
	v_lshl_add_u64 v[220:221], v[220:221], 0, s[16:17]
	s_mov_b32 m0, s0
	ds_read_b128 v[178:181], v189 offset:49152
	ds_read_b128 v[192:195], v189 offset:50176
	ds_read_b128 v[196:199], v189 offset:51200
	ds_read_b128 v[200:203], v189 offset:52224
	ds_read_b128 v[204:207], v189 offset:53248
	ds_read_b128 v[208:211], v189 offset:54272
	ds_read_b128 v[212:215], v189 offset:55296
	ds_read_b128 v[216:219], v189 offset:56320
	global_load_lds_dwordx4 v[220:221], off
	s_add_i32 m0, s0, 0x2000
	s_add_u32 s0, s2, 0xb0080
	v_lshl_add_u64 v[220:221], v[222:223], 0, s[16:17]
	s_addc_u32 s1, s3, 0
	s_add_i32 s2, s49, s30
	global_load_lds_dwordx4 v[220:221], off
	v_lshl_add_u64 v[220:221], s[0:1], 0, v[156:157]
	s_mov_b32 m0, s2
	s_nop 0
	global_load_lds_dwordx4 v[220:221], off
	v_lshl_add_u64 v[220:221], s[0:1], 0, v[160:161]
	s_add_i32 m0, s2, 0x2000
	s_nop 0
	global_load_lds_dwordx4 v[220:221], off
	v_lshl_add_u64 v[220:221], v[224:225], 0, s[16:17]
	s_mov_b32 m0, s37
	s_nop 0
	global_load_lds_dwordx4 v[220:221], off
	v_lshl_add_u64 v[220:221], v[226:227], 0, s[16:17]
	s_mov_b32 m0, s38
	s_nop 0
	global_load_lds_dwordx4 v[220:221], off
	s_waitcnt vmcnt(8)
	s_waitcnt lgkmcnt(0)
	s_barrier
	s_setprio 1
	s_waitcnt lgkmcnt(0)
	v_mfma_f32_16x16x32_bf16 v[62:65], v[130:133], v[178:181], v[62:65]
	v_mfma_f32_16x16x32_bf16 v[62:65], v[134:137], v[192:195], v[62:65]
	v_mfma_f32_16x16x32_bf16 v[58:61], v[138:141], v[178:181], v[58:61]
	v_mfma_f32_16x16x32_bf16 v[58:61], v[142:145], v[192:195], v[58:61]
	v_mfma_f32_16x16x32_bf16 v[46:49], v[130:133], v[196:199], v[46:49]
	v_mfma_f32_16x16x32_bf16 v[46:49], v[134:137], v[200:203], v[46:49]
	v_mfma_f32_16x16x32_bf16 v[42:45], v[138:141], v[196:199], v[42:45]
	v_mfma_f32_16x16x32_bf16 v[42:45], v[142:145], v[200:203], v[42:45]
	v_mfma_f32_16x16x32_bf16 v[30:33], v[130:133], v[204:207], v[30:33]
	v_mfma_f32_16x16x32_bf16 v[30:33], v[134:137], v[208:211], v[30:33]
	v_mfma_f32_16x16x32_bf16 v[26:29], v[138:141], v[204:207], v[26:29]
	v_mfma_f32_16x16x32_bf16 v[26:29], v[142:145], v[208:211], v[26:29]
	v_mfma_f32_16x16x32_bf16 v[14:17], v[130:133], v[212:215], v[14:17]
	v_mfma_f32_16x16x32_bf16 v[14:17], v[134:137], v[216:219], v[14:17]
	v_mfma_f32_16x16x32_bf16 v[10:13], v[138:141], v[212:215], v[10:13]
	v_mfma_f32_16x16x32_bf16 v[10:13], v[142:145], v[216:219], v[10:13]
	s_setprio 0
	s_setprio 1
	v_mfma_f32_16x16x32_bf16 v[54:57], v[146:149], v[178:181], v[54:57]
	v_mfma_f32_16x16x32_bf16 v[54:57], v[150:153], v[192:195], v[54:57]
	v_mfma_f32_16x16x32_bf16 v[50:53], v[170:173], v[178:181], v[50:53]
	v_mfma_f32_16x16x32_bf16 v[50:53], v[174:177], v[192:195], v[50:53]
	v_mfma_f32_16x16x32_bf16 v[38:41], v[146:149], v[196:199], v[38:41]
	v_mfma_f32_16x16x32_bf16 v[38:41], v[150:153], v[200:203], v[38:41]
	v_mfma_f32_16x16x32_bf16 v[34:37], v[170:173], v[196:199], v[34:37]
	v_mfma_f32_16x16x32_bf16 v[34:37], v[174:177], v[200:203], v[34:37]
	v_mfma_f32_16x16x32_bf16 v[22:25], v[146:149], v[204:207], v[22:25]
	v_mfma_f32_16x16x32_bf16 v[22:25], v[150:153], v[208:211], v[22:25]
	v_mfma_f32_16x16x32_bf16 v[18:21], v[170:173], v[204:207], v[18:21]
	v_mfma_f32_16x16x32_bf16 v[18:21], v[174:177], v[208:211], v[18:21]
	v_mfma_f32_16x16x32_bf16 v[6:9], v[146:149], v[212:215], v[6:9]
	v_mfma_f32_16x16x32_bf16 v[6:9], v[150:153], v[216:219], v[6:9]
	v_mfma_f32_16x16x32_bf16 v[2:5], v[170:173], v[212:215], v[2:5]
	v_mfma_f32_16x16x32_bf16 v[2:5], v[174:177], v[216:219], v[2:5]
	s_setprio 0
	s_barrier
	s_add_i32 s47, s47, 2
	s_add_u32 s22, s22, 0x100
	s_addc_u32 s23, s23, 0
	s_add_u32 s45, s45, 0x100
	s_addc_u32 s46, s46, 0
	s_cmp_gt_u32 s47, 41
	s_cbranch_scc0 .LBB0_584
	s_and_b64 vcc, exec, s[18:19]
	s_cbranch_vccz .LBB0_587
	s_barrier

.LBB0_913:
	v_lshl_add_u32 v238, s26, 8, v182
	v_lshlrev_b32_e32 v238, 11, v238
	v_mov_b32_e32 v239, 0
	v_lshl_or_b32 v240, s10, 8, v184
	v_lshlrev_b32_e32 v240, 1, v240
	v_mov_b32_e32 v241, 0
	v_lshl_add_u64 v[240:241], s[78:79], 0, v[240:241]
	v_lshl_add_u64 v[238:239], v[240:241], 0, v[238:239]
	v_mov_b32_e32 v242, 0x8000
	v_mov_b32_e32 v243, 0
	global_load_dwordx4 v[246:249], v[238:239], off
	global_load_dwordx4 v[246:249], v[238:239], off offset:256
	v_lshl_add_u64 v[238:239], v[238:239], 0, v[242:243]
	global_load_dwordx4 v[246:249], v[238:239], off
	global_load_dwordx4 v[246:249], v[238:239], off offset:256
	v_lshl_add_u64 v[238:239], v[238:239], 0, v[242:243]
	global_load_dwordx4 v[246:249], v[238:239], off
	global_load_dwordx4 v[246:249], v[238:239], off offset:256
	v_lshl_add_u64 v[238:239], v[238:239], 0, v[242:243]
	global_load_dwordx4 v[246:249], v[238:239], off
	global_load_dwordx4 v[246:249], v[238:239], off offset:256
	s_add_i32 s41, s41, 1
	s_mul_i32 s0, s41, s44
	s_mul_hi_u32 s1, s41, s75
	s_add_i32 s1, s1, s0
	s_mul_i32 s0, s41, s75
	s_add_u32 s22, s0, s64
	s_addc_u32 s23, s1, s45
	v_cmp_gt_i64_e32 vcc, s[22:23], v[168:169]
	v_cmp_lt_i64_e64 s[6:7], s[22:23], v[166:167]
	s_cbranch_vccnz .LBB0_919
	s_ashr_i32 s0, s22, 31
	s_lshr_b32 s0, s0, 29
	s_add_i32 s0, s22, s0
	s_and_b32 s1, s0, -8
	s_sub_i32 s1, s22, s1
	s_cmp_gt_i32 s1, -1
	s_mov_b64 s[18:19], -1
	s_cbranch_scc0 .LBB0_916
	s_lshl_b32 s11, s1, 5
	s_mov_b64 s[18:19], 0

.LBB0_919:
	s_ashr_i32 s21, s20, 31
	s_lshl_b64 s[0:1], s[20:21], 19
	s_add_u32 s22, s33, s0
	s_addc_u32 s23, s34, s1
	s_and_b64 s[0:1], s[6:7], exec
	s_cselect_b32 s11, s23, s29
	s_cselect_b32 s21, s22, s28
	s_ashr_i32 s19, s18, 31
	s_lshl_b64 s[0:1], s[18:19], 19
	s_add_u32 s24, s35, s0
	s_addc_u32 s25, s36, s1
	s_and_b64 s[0:1], s[6:7], exec
	s_cselect_b32 s19, s25, s3
	s_cselect_b32 s48, s24, s2
	s_add_u32 s28, s28, 0x40080
	s_addc_u32 s29, s29, 0
	s_add_u32 s49, s2, 0x100
	v_mov_b32_e32 v2, 0
	s_addc_u32 s50, s3, 0
	s_mov_b32 s51, -2
	s_waitcnt lgkmcnt(0)
	v_mov_b32_e32 v3, v2
	v_mov_b32_e32 v4, v2
	v_mov_b32_e32 v5, v2
	v_mov_b32_e32 v6, v2
	v_mov_b32_e32 v7, v2
	v_mov_b32_e32 v8, v2
	v_mov_b32_e32 v9, v2
	v_mov_b32_e32 v18, v2
	v_mov_b32_e32 v19, v2
	v_mov_b32_e32 v20, v2
	v_mov_b32_e32 v21, v2
	v_mov_b32_e32 v22, v2
	v_mov_b32_e32 v23, v2
	v_mov_b32_e32 v24, v2
	v_mov_b32_e32 v25, v2
	v_mov_b32_e32 v34, v2
	v_mov_b32_e32 v35, v2
	v_mov_b32_e32 v36, v2
	v_mov_b32_e32 v37, v2
	v_mov_b32_e32 v38, v2
	v_mov_b32_e32 v39, v2
	v_mov_b32_e32 v40, v2
	v_mov_b32_e32 v41, v2
	v_mov_b32_e32 v50, v2
	v_mov_b32_e32 v51, v2
	v_mov_b32_e32 v52, v2
	v_mov_b32_e32 v53, v2
	v_mov_b32_e32 v54, v2
	v_mov_b32_e32 v55, v2
	v_mov_b32_e32 v56, v2
	v_mov_b32_e32 v57, v2
	v_mov_b32_e32 v10, v2
	v_mov_b32_e32 v11, v2
	v_mov_b32_e32 v12, v2
	v_mov_b32_e32 v13, v2
	v_mov_b32_e32 v14, v2
	v_mov_b32_e32 v15, v2
	v_mov_b32_e32 v16, v2
	v_mov_b32_e32 v17, v2
	v_mov_b32_e32 v26, v2
	v_mov_b32_e32 v27, v2
	v_mov_b32_e32 v28, v2
	v_mov_b32_e32 v29, v2
	v_mov_b32_e32 v30, v2
	v_mov_b32_e32 v31, v2
	v_mov_b32_e32 v32, v2
	v_mov_b32_e32 v33, v2
	v_mov_b32_e32 v42, v2
	v_mov_b32_e32 v43, v2
	v_mov_b32_e32 v44, v2
	v_mov_b32_e32 v45, v2
	v_mov_b32_e32 v46, v2
	v_mov_b32_e32 v47, v2
	v_mov_b32_e32 v48, v2
	v_mov_b32_e32 v49, v2
	v_mov_b32_e32 v58, v2
	v_mov_b32_e32 v59, v2
	v_mov_b32_e32 v60, v2
	v_mov_b32_e32 v61, v2
	v_mov_b32_e32 v62, v2
	v_mov_b32_e32 v63, v2
	v_mov_b32_e32 v64, v2
	v_mov_b32_e32 v65, v2
	v_mov_b32_e32 v66, v2
	v_mov_b32_e32 v67, v2
	v_mov_b32_e32 v68, v2
	v_mov_b32_e32 v69, v2
	v_mov_b32_e32 v70, v2
	v_mov_b32_e32 v71, v2
	v_mov_b32_e32 v72, v2
	v_mov_b32_e32 v73, v2
	v_mov_b32_e32 v82, v2
	v_mov_b32_e32 v83, v2
	v_mov_b32_e32 v84, v2
	v_mov_b32_e32 v85, v2
	v_mov_b32_e32 v86, v2
	v_mov_b32_e32 v87, v2
	v_mov_b32_e32 v88, v2
	v_mov_b32_e32 v89, v2
	v_mov_b32_e32 v98, v2
	v_mov_b32_e32 v99, v2
	v_mov_b32_e32 v100, v2
	v_mov_b32_e32 v101, v2
	v_mov_b32_e32 v102, v2
	v_mov_b32_e32 v103, v2
	v_mov_b32_e32 v104, v2
	v_mov_b32_e32 v105, v2
	v_mov_b32_e32 v114, v2
	v_mov_b32_e32 v115, v2
	v_mov_b32_e32 v116, v2
	v_mov_b32_e32 v117, v2
	v_mov_b32_e32 v118, v2
	v_mov_b32_e32 v119, v2
	v_mov_b32_e32 v120, v2
	v_mov_b32_e32 v121, v2
	v_mov_b32_e32 v74, v2
	v_mov_b32_e32 v75, v2
	v_mov_b32_e32 v76, v2
	v_mov_b32_e32 v77, v2
	v_mov_b32_e32 v78, v2
	v_mov_b32_e32 v79, v2
	v_mov_b32_e32 v80, v2
	v_mov_b32_e32 v81, v2
	v_mov_b32_e32 v90, v2
	v_mov_b32_e32 v91, v2
	v_mov_b32_e32 v92, v2
	v_mov_b32_e32 v93, v2
	v_mov_b32_e32 v94, v2
	v_mov_b32_e32 v95, v2
	v_mov_b32_e32 v96, v2
	v_mov_b32_e32 v97, v2
	v_mov_b32_e32 v106, v2
	v_mov_b32_e32 v107, v2
	v_mov_b32_e32 v108, v2
	v_mov_b32_e32 v109, v2
	v_mov_b32_e32 v110, v2
	v_mov_b32_e32 v111, v2
	v_mov_b32_e32 v112, v2
	v_mov_b32_e32 v113, v2
	v_mov_b32_e32 v122, v2
	v_mov_b32_e32 v123, v2
	v_mov_b32_e32 v124, v2
	v_mov_b32_e32 v125, v2
	v_mov_b32_e32 v126, v2
	v_mov_b32_e32 v127, v2
	v_mov_b32_e32 v128, v2
	v_mov_b32_e32 v129, v2
	s_nop 0
	s_nop 0
	s_nop 0
	s_nop 0
	s_nop 0
	s_nop 0
	s_nop 0
	s_nop 0
	s_nop 0
	s_nop 0
	s_nop 0

.LBB0_1112:
	v_lshl_add_u32 v238, s13, 8, v182
	v_lshlrev_b32_e32 v238, 11, v238
	v_mov_b32_e32 v239, 0
	v_lshl_or_b32 v240, s12, 8, v184
	v_lshlrev_b32_e32 v240, 1, v240
	v_mov_b32_e32 v241, 0
	v_lshl_add_u64 v[240:241], s[78:79], 0, v[240:241]
	v_lshl_add_u64 v[238:239], v[240:241], 0, v[238:239]
	v_mov_b32_e32 v242, 0x8000
	v_mov_b32_e32 v243, 0
	global_load_dwordx4 v[246:249], v[238:239], off
	global_load_dwordx4 v[246:249], v[238:239], off offset:256
	v_lshl_add_u64 v[238:239], v[238:239], 0, v[242:243]
	global_load_dwordx4 v[246:249], v[238:239], off
	global_load_dwordx4 v[246:249], v[238:239], off offset:256
	v_lshl_add_u64 v[238:239], v[238:239], 0, v[242:243]
	global_load_dwordx4 v[246:249], v[238:239], off
	global_load_dwordx4 v[246:249], v[238:239], off offset:256
	v_lshl_add_u64 v[238:239], v[238:239], 0, v[242:243]
	global_load_dwordx4 v[246:249], v[238:239], off
	global_load_dwordx4 v[246:249], v[238:239], off offset:256
	s_add_i32 s38, s38, 1
	s_mul_i32 s0, s38, s41
	s_mul_hi_u32 s1, s38, s75
	s_add_i32 s1, s1, s0
	s_mul_i32 s0, s38, s75
	s_add_u32 s6, s0, s64
	s_addc_u32 s7, s1, s42
	v_cmp_gt_i64_e32 vcc, s[6:7], v[168:169]
	v_cmp_lt_i64_e64 s[8:9], s[6:7], v[166:167]
	s_cbranch_vccnz .LBB0_1118
	s_ashr_i32 s0, s6, 31
	s_lshr_b32 s0, s0, 29
	s_add_i32 s0, s6, s0
	s_and_b32 s1, s0, -8
	s_sub_i32 s1, s6, s1
	s_cmp_gt_i32 s1, -1
	s_mov_b64 s[6:7], -1
	s_cbranch_scc0 .LBB0_1115
	s_lshl_b32 s22, s1, 5
	s_mov_b64 s[6:7], 0

.LBB0_1122:
	s_add_u32 s24, s24, 0xb0080
	s_addc_u32 s25, s25, 0
	s_add_u32 s47, s2, 0x100
	v_mov_b32_e32 v2, 0
	s_addc_u32 s48, s3, 0
	s_mov_b32 s49, -2
	s_waitcnt lgkmcnt(0)
	v_mov_b32_e32 v3, v2
	v_mov_b32_e32 v4, v2
	v_mov_b32_e32 v5, v2
	v_mov_b32_e32 v6, v2
	v_mov_b32_e32 v7, v2
	v_mov_b32_e32 v8, v2
	v_mov_b32_e32 v9, v2
	v_mov_b32_e32 v18, v2
	v_mov_b32_e32 v19, v2
	v_mov_b32_e32 v20, v2
	v_mov_b32_e32 v21, v2
	v_mov_b32_e32 v22, v2
	v_mov_b32_e32 v23, v2
	v_mov_b32_e32 v24, v2
	v_mov_b32_e32 v25, v2
	v_mov_b32_e32 v34, v2
	v_mov_b32_e32 v35, v2
	v_mov_b32_e32 v36, v2
	v_mov_b32_e32 v37, v2
	v_mov_b32_e32 v38, v2
	v_mov_b32_e32 v39, v2
	v_mov_b32_e32 v40, v2
	v_mov_b32_e32 v41, v2
	v_mov_b32_e32 v50, v2
	v_mov_b32_e32 v51, v2
	v_mov_b32_e32 v52, v2
	v_mov_b32_e32 v53, v2
	v_mov_b32_e32 v54, v2
	v_mov_b32_e32 v55, v2
	v_mov_b32_e32 v56, v2
	v_mov_b32_e32 v57, v2
	v_mov_b32_e32 v10, v2
	v_mov_b32_e32 v11, v2
	v_mov_b32_e32 v12, v2
	v_mov_b32_e32 v13, v2
	v_mov_b32_e32 v14, v2
	v_mov_b32_e32 v15, v2
	v_mov_b32_e32 v16, v2
	v_mov_b32_e32 v17, v2
	v_mov_b32_e32 v26, v2
	v_mov_b32_e32 v27, v2
	v_mov_b32_e32 v28, v2
	v_mov_b32_e32 v29, v2
	v_mov_b32_e32 v30, v2
	v_mov_b32_e32 v31, v2
	v_mov_b32_e32 v32, v2
	v_mov_b32_e32 v33, v2
	v_mov_b32_e32 v42, v2
	v_mov_b32_e32 v43, v2
	v_mov_b32_e32 v44, v2
	v_mov_b32_e32 v45, v2
	v_mov_b32_e32 v46, v2
	v_mov_b32_e32 v47, v2
	v_mov_b32_e32 v48, v2
	v_mov_b32_e32 v49, v2
	v_mov_b32_e32 v58, v2
	v_mov_b32_e32 v59, v2
	v_mov_b32_e32 v60, v2
	v_mov_b32_e32 v61, v2
	v_mov_b32_e32 v62, v2
	v_mov_b32_e32 v63, v2
	v_mov_b32_e32 v64, v2
	v_mov_b32_e32 v65, v2
	v_mov_b32_e32 v66, v2
	v_mov_b32_e32 v67, v2
	v_mov_b32_e32 v68, v2
	v_mov_b32_e32 v69, v2
	v_mov_b32_e32 v70, v2
	v_mov_b32_e32 v71, v2
	v_mov_b32_e32 v72, v2
	v_mov_b32_e32 v73, v2
	v_mov_b32_e32 v82, v2
	v_mov_b32_e32 v83, v2
	v_mov_b32_e32 v84, v2
	v_mov_b32_e32 v85, v2
	v_mov_b32_e32 v86, v2
	v_mov_b32_e32 v87, v2
	v_mov_b32_e32 v88, v2
	v_mov_b32_e32 v89, v2
	v_mov_b32_e32 v98, v2
	v_mov_b32_e32 v99, v2
	v_mov_b32_e32 v100, v2
	v_mov_b32_e32 v101, v2
	v_mov_b32_e32 v102, v2
	v_mov_b32_e32 v103, v2
	v_mov_b32_e32 v104, v2
	v_mov_b32_e32 v105, v2
	v_mov_b32_e32 v114, v2
	v_mov_b32_e32 v115, v2
	v_mov_b32_e32 v116, v2
	v_mov_b32_e32 v117, v2
	v_mov_b32_e32 v118, v2
	v_mov_b32_e32 v119, v2
	v_mov_b32_e32 v120, v2
	v_mov_b32_e32 v121, v2
	v_mov_b32_e32 v74, v2
	v_mov_b32_e32 v75, v2
	v_mov_b32_e32 v76, v2
	v_mov_b32_e32 v77, v2
	v_mov_b32_e32 v78, v2
	v_mov_b32_e32 v79, v2
	v_mov_b32_e32 v80, v2
	v_mov_b32_e32 v81, v2
	v_mov_b32_e32 v90, v2
	v_mov_b32_e32 v91, v2
	v_mov_b32_e32 v92, v2
	v_mov_b32_e32 v93, v2
	v_mov_b32_e32 v94, v2
	v_mov_b32_e32 v95, v2
	v_mov_b32_e32 v96, v2
	v_mov_b32_e32 v97, v2
	v_mov_b32_e32 v106, v2
	v_mov_b32_e32 v107, v2
	v_mov_b32_e32 v108, v2
	v_mov_b32_e32 v109, v2
	v_mov_b32_e32 v110, v2
	v_mov_b32_e32 v111, v2
	v_mov_b32_e32 v112, v2
	v_mov_b32_e32 v113, v2
	v_mov_b32_e32 v122, v2
	v_mov_b32_e32 v123, v2
	v_mov_b32_e32 v124, v2
	v_mov_b32_e32 v125, v2
	v_mov_b32_e32 v126, v2
	v_mov_b32_e32 v127, v2
	v_mov_b32_e32 v128, v2
	v_mov_b32_e32 v129, v2
	s_nop 0
	s_nop 0
	s_nop 0
	s_nop 0
	s_nop 0
	s_nop 0
	s_nop 0
	s_nop 0
	s_nop 0
	s_nop 0
	s_nop 0

.LBB0_1619:
	v_lshl_add_u32 v238, s36, 8, v1
	v_lshlrev_b32_e32 v238, 11, v238
	v_mov_b32_e32 v239, 0
	v_lshl_or_b32 v240, s10, 8, v183
	v_lshlrev_b32_e32 v240, 1, v240
	v_mov_b32_e32 v241, 0
	v_lshl_add_u64 v[240:241], s[78:79], 0, v[240:241]
	v_lshl_add_u64 v[238:239], v[240:241], 0, v[238:239]
	v_mov_b32_e32 v242, 0x8000
	v_mov_b32_e32 v243, 0
	global_load_dwordx4 v[246:249], v[238:239], off
	global_load_dwordx4 v[246:249], v[238:239], off offset:256
	v_lshl_add_u64 v[238:239], v[238:239], 0, v[242:243]
	global_load_dwordx4 v[246:249], v[238:239], off
	global_load_dwordx4 v[246:249], v[238:239], off offset:256
	v_lshl_add_u64 v[238:239], v[238:239], 0, v[242:243]
	global_load_dwordx4 v[246:249], v[238:239], off
	global_load_dwordx4 v[246:249], v[238:239], off offset:256
	v_lshl_add_u64 v[238:239], v[238:239], 0, v[242:243]
	global_load_dwordx4 v[246:249], v[238:239], off
	global_load_dwordx4 v[246:249], v[238:239], off offset:256
	s_add_i32 s49, s49, 1
	s_mul_i32 s0, s49, s52
	s_mul_hi_u32 s1, s49, s75
	s_add_i32 s1, s1, s0
	s_mul_i32 s0, s49, s75
	s_add_u32 s30, s0, s64
	s_addc_u32 s31, s1, s53
	v_cmp_gt_i64_e32 vcc, s[30:31], v[168:169]
	v_cmp_lt_i64_e64 s[6:7], s[30:31], v[166:167]
	s_cbranch_vccnz .LBB0_1625
	s_ashr_i32 s0, s30, 31
	s_lshr_b32 s0, s0, 29
	s_add_i32 s0, s30, s0
	s_and_b32 s1, s0, -8
	s_sub_i32 s1, s30, s1
	s_cmp_gt_i32 s1, -1
	s_mov_b64 s[26:27], -1
	s_cbranch_scc0 .LBB0_1622
	s_lshl_b32 s11, s1, 5
	s_mov_b64 s[26:27], 0

.LBB0_1625:
	s_ashr_i32 s29, s28, 31
	s_lshl_b64 s[0:1], s[28:29], 20
	s_add_u32 s30, s33, s0
	s_addc_u32 s31, s42, s1
	s_and_b64 s[0:1], s[6:7], exec
	s_cselect_b32 s11, s31, s39
	s_cselect_b32 s29, s30, s38
	s_ashr_i32 s27, s26, 31
	s_lshl_b64 s[0:1], s[26:27], 20
	s_add_u32 s34, s43, s0
	s_addc_u32 s35, s44, s1
	s_and_b64 s[0:1], s[6:7], exec
	s_cselect_b32 s27, s35, s3
	s_cselect_b32 s56, s34, s2
	s_add_u32 s38, s38, 0x80080
	s_addc_u32 s39, s39, 0
	s_add_u32 s57, s2, 0x100
	v_mov_b32_e32 v2, 0
	s_addc_u32 s58, s3, 0
	s_mov_b32 s59, -2
	s_waitcnt lgkmcnt(0)
	v_mov_b32_e32 v3, v2
	v_mov_b32_e32 v4, v2
	v_mov_b32_e32 v5, v2
	v_mov_b32_e32 v6, v2
	v_mov_b32_e32 v7, v2
	v_mov_b32_e32 v8, v2
	v_mov_b32_e32 v9, v2
	v_mov_b32_e32 v18, v2
	v_mov_b32_e32 v19, v2
	v_mov_b32_e32 v20, v2
	v_mov_b32_e32 v21, v2
	v_mov_b32_e32 v22, v2
	v_mov_b32_e32 v23, v2
	v_mov_b32_e32 v24, v2
	v_mov_b32_e32 v25, v2
	v_mov_b32_e32 v34, v2
	v_mov_b32_e32 v35, v2
	v_mov_b32_e32 v36, v2
	v_mov_b32_e32 v37, v2
	v_mov_b32_e32 v38, v2
	v_mov_b32_e32 v39, v2
	v_mov_b32_e32 v40, v2
	v_mov_b32_e32 v41, v2
	v_mov_b32_e32 v50, v2
	v_mov_b32_e32 v51, v2
	v_mov_b32_e32 v52, v2
	v_mov_b32_e32 v53, v2
	v_mov_b32_e32 v54, v2
	v_mov_b32_e32 v55, v2
	v_mov_b32_e32 v56, v2
	v_mov_b32_e32 v57, v2
	v_mov_b32_e32 v10, v2
	v_mov_b32_e32 v11, v2
	v_mov_b32_e32 v12, v2
	v_mov_b32_e32 v13, v2
	v_mov_b32_e32 v14, v2
	v_mov_b32_e32 v15, v2
	v_mov_b32_e32 v16, v2
	v_mov_b32_e32 v17, v2
	v_mov_b32_e32 v26, v2
	v_mov_b32_e32 v27, v2
	v_mov_b32_e32 v28, v2
	v_mov_b32_e32 v29, v2
	v_mov_b32_e32 v30, v2
	v_mov_b32_e32 v31, v2
	v_mov_b32_e32 v32, v2
	v_mov_b32_e32 v33, v2
	v_mov_b32_e32 v42, v2
	v_mov_b32_e32 v43, v2
	v_mov_b32_e32 v44, v2
	v_mov_b32_e32 v45, v2
	v_mov_b32_e32 v46, v2
	v_mov_b32_e32 v47, v2
	v_mov_b32_e32 v48, v2
	v_mov_b32_e32 v49, v2
	v_mov_b32_e32 v58, v2
	v_mov_b32_e32 v59, v2
	v_mov_b32_e32 v60, v2
	v_mov_b32_e32 v61, v2
	v_mov_b32_e32 v62, v2
	v_mov_b32_e32 v63, v2
	v_mov_b32_e32 v64, v2
	v_mov_b32_e32 v65, v2
	v_mov_b32_e32 v66, v2
	v_mov_b32_e32 v67, v2
	v_mov_b32_e32 v68, v2
	v_mov_b32_e32 v69, v2
	v_mov_b32_e32 v70, v2
	v_mov_b32_e32 v71, v2
	v_mov_b32_e32 v72, v2
	v_mov_b32_e32 v73, v2
	v_mov_b32_e32 v82, v2
	v_mov_b32_e32 v83, v2
	v_mov_b32_e32 v84, v2
	v_mov_b32_e32 v85, v2
	v_mov_b32_e32 v86, v2
	v_mov_b32_e32 v87, v2
	v_mov_b32_e32 v88, v2
	v_mov_b32_e32 v89, v2
	v_mov_b32_e32 v98, v2
	v_mov_b32_e32 v99, v2
	v_mov_b32_e32 v100, v2
	v_mov_b32_e32 v101, v2
	v_mov_b32_e32 v102, v2
	v_mov_b32_e32 v103, v2
	v_mov_b32_e32 v104, v2
	v_mov_b32_e32 v105, v2
	v_mov_b32_e32 v114, v2
	v_mov_b32_e32 v115, v2
	v_mov_b32_e32 v116, v2
	v_mov_b32_e32 v117, v2
	v_mov_b32_e32 v118, v2
	v_mov_b32_e32 v119, v2
	v_mov_b32_e32 v120, v2
	v_mov_b32_e32 v121, v2
	v_mov_b32_e32 v74, v2
	v_mov_b32_e32 v75, v2
	v_mov_b32_e32 v76, v2
	v_mov_b32_e32 v77, v2
	v_mov_b32_e32 v78, v2
	v_mov_b32_e32 v79, v2
	v_mov_b32_e32 v80, v2
	v_mov_b32_e32 v81, v2
	v_mov_b32_e32 v90, v2
	v_mov_b32_e32 v91, v2
	v_mov_b32_e32 v92, v2
	v_mov_b32_e32 v93, v2
	v_mov_b32_e32 v94, v2
	v_mov_b32_e32 v95, v2
	v_mov_b32_e32 v96, v2
	v_mov_b32_e32 v97, v2
	v_mov_b32_e32 v106, v2
	v_mov_b32_e32 v107, v2
	v_mov_b32_e32 v108, v2
	v_mov_b32_e32 v109, v2
	v_mov_b32_e32 v110, v2
	v_mov_b32_e32 v111, v2
	v_mov_b32_e32 v112, v2
	v_mov_b32_e32 v113, v2
	v_mov_b32_e32 v122, v2
	v_mov_b32_e32 v123, v2
	v_mov_b32_e32 v124, v2
	v_mov_b32_e32 v125, v2
	v_mov_b32_e32 v126, v2
	v_mov_b32_e32 v127, v2
	v_mov_b32_e32 v128, v2
	v_mov_b32_e32 v129, v2
.LBB0_1626:
	ds_read_b128 v[130:133], v186
	ds_read_b128 v[134:137], v186 offset:1024
	ds_read_b128 v[138:141], v186 offset:2048
	ds_read_b128 v[142:145], v186 offset:3072
	ds_read_b128 v[146:149], v187
	ds_read_b128 v[150:153], v187 offset:1024
	ds_read_b128 v[170:173], v187 offset:2048
	ds_read_b128 v[174:177], v187 offset:3072
	s_add_u32 s0, s38, 0xfff80080
	s_addc_u32 s1, s39, -1
	s_cmp_eq_u32 s59, 28
	s_cselect_b32 s41, s11, s1
	s_cselect_b32 s40, s29, s0
	s_cselect_b32 s3, s27, s58
	s_cselect_b32 s2, s56, s57
	v_lshl_add_u64 v[218:219], s[38:39], 0, v[162:163]
	s_add_i32 m0, s37, 0xc000
	ds_read_b128 v[178:181], v188
	ds_read_b128 v[190:193], v188 offset:1024
	ds_read_b128 v[194:197], v188 offset:2048
	ds_read_b128 v[198:201], v188 offset:3072
	ds_read_b128 v[202:205], v188 offset:4096
	ds_read_b128 v[206:209], v188 offset:5120
	ds_read_b128 v[210:213], v188 offset:6144
	ds_read_b128 v[214:217], v188 offset:7168
	global_load_lds_dwordx4 v[218:219], off
	v_lshl_add_u64 v[218:219], s[38:39], 0, v[164:165]
	s_add_i32 m0, s37, 0xe000
	s_nop 0
	global_load_lds_dwordx4 v[218:219], off
	s_waitcnt vmcnt(8)
	s_waitcnt lgkmcnt(0)
	s_barrier
	s_setprio 1
	s_waitcnt lgkmcnt(0)
	v_mfma_f32_16x16x32_bf16 v[126:129], v[130:133], v[178:181], v[126:129]
	v_mfma_f32_16x16x32_bf16 v[126:129], v[134:137], v[190:193], v[126:129]
	v_mfma_f32_16x16x32_bf16 v[122:125], v[138:141], v[178:181], v[122:125]
	v_mfma_f32_16x16x32_bf16 v[122:125], v[142:145], v[190:193], v[122:125]
	v_mfma_f32_16x16x32_bf16 v[110:113], v[130:133], v[194:197], v[110:113]
	v_mfma_f32_16x16x32_bf16 v[110:113], v[134:137], v[198:201], v[110:113]
	v_mfma_f32_16x16x32_bf16 v[106:109], v[138:141], v[194:197], v[106:109]
	v_mfma_f32_16x16x32_bf16 v[106:109], v[142:145], v[198:201], v[106:109]
	v_mfma_f32_16x16x32_bf16 v[94:97], v[130:133], v[202:205], v[94:97]
	v_mfma_f32_16x16x32_bf16 v[94:97], v[134:137], v[206:209], v[94:97]
	v_mfma_f32_16x16x32_bf16 v[90:93], v[138:141], v[202:205], v[90:93]
	v_mfma_f32_16x16x32_bf16 v[90:93], v[142:145], v[206:209], v[90:93]
	v_mfma_f32_16x16x32_bf16 v[78:81], v[130:133], v[210:213], v[78:81]
	v_mfma_f32_16x16x32_bf16 v[78:81], v[134:137], v[214:217], v[78:81]
	v_mfma_f32_16x16x32_bf16 v[74:77], v[138:141], v[210:213], v[74:77]
	v_mfma_f32_16x16x32_bf16 v[74:77], v[142:145], v[214:217], v[74:77]
	s_setprio 0
	s_setprio 1
	v_mfma_f32_16x16x32_bf16 v[118:121], v[146:149], v[178:181], v[118:121]
	v_mfma_f32_16x16x32_bf16 v[118:121], v[150:153], v[190:193], v[118:121]
	v_mfma_f32_16x16x32_bf16 v[114:117], v[170:173], v[178:181], v[114:117]
	v_mfma_f32_16x16x32_bf16 v[114:117], v[174:177], v[190:193], v[114:117]
	v_mfma_f32_16x16x32_bf16 v[102:105], v[146:149], v[194:197], v[102:105]
	v_mfma_f32_16x16x32_bf16 v[102:105], v[150:153], v[198:201], v[102:105]
	v_mfma_f32_16x16x32_bf16 v[98:101], v[170:173], v[194:197], v[98:101]
	v_mfma_f32_16x16x32_bf16 v[98:101], v[174:177], v[198:201], v[98:101]
	v_mfma_f32_16x16x32_bf16 v[86:89], v[146:149], v[202:205], v[86:89]
	v_mfma_f32_16x16x32_bf16 v[86:89], v[150:153], v[206:209], v[86:89]
	v_mfma_f32_16x16x32_bf16 v[82:85], v[170:173], v[202:205], v[82:85]
	v_mfma_f32_16x16x32_bf16 v[82:85], v[174:177], v[206:209], v[82:85]
	v_mfma_f32_16x16x32_bf16 v[70:73], v[146:149], v[210:213], v[70:73]
	v_mfma_f32_16x16x32_bf16 v[70:73], v[150:153], v[214:217], v[70:73]
	v_mfma_f32_16x16x32_bf16 v[66:69], v[170:173], v[210:213], v[66:69]
	v_mfma_f32_16x16x32_bf16 v[66:69], v[174:177], v[214:217], v[66:69]
	s_setprio 0
	s_barrier
	s_add_i32 s0, s54, s45
	v_lshl_add_u64 v[218:219], s[2:3], 0, v[156:157]
	s_mov_b32 m0, s0
	ds_read_b128 v[178:181], v188 offset:16384
	ds_read_b128 v[190:193], v188 offset:17408
	ds_read_b128 v[194:197], v188 offset:18432
	ds_read_b128 v[198:201], v188 offset:19456
	ds_read_b128 v[202:205], v188 offset:20480
	ds_read_b128 v[206:209], v188 offset:21504
	ds_read_b128 v[210:213], v188 offset:22528
	ds_read_b128 v[214:217], v188 offset:23552
	global_load_lds_dwordx4 v[218:219], off
	s_add_i32 m0, s0, 0x2000
	s_add_u32 s0, s2, 0x80000
	v_lshl_add_u64 v[220:221], s[2:3], 0, v[160:161]
	s_addc_u32 s1, s3, 0
	s_add_i32 s60, s55, s45
	global_load_lds_dwordx4 v[220:221], off
	v_lshl_add_u64 v[222:223], s[0:1], 0, v[156:157]
	s_mov_b32 m0, s60
	v_lshl_add_u64 v[224:225], s[40:41], 0, v[158:159]
	global_load_lds_dwordx4 v[222:223], off
	v_lshl_add_u64 v[222:223], s[0:1], 0, v[160:161]
	s_add_i32 m0, s60, 0x2000
	s_nop 0
	global_load_lds_dwordx4 v[222:223], off
	v_lshl_add_u64 v[222:223], s[40:41], 0, v[154:155]
	s_mov_b32 m0, s37
	s_nop 0
	global_load_lds_dwordx4 v[222:223], off
	s_mov_b32 m0, s46
	s_nop 0
	global_load_lds_dwordx4 v[224:225], off
	s_waitcnt vmcnt(8)
	s_waitcnt lgkmcnt(0)
	s_barrier
	s_setprio 1
	s_waitcnt lgkmcnt(0)
	v_mfma_f32_16x16x32_bf16 v[62:65], v[130:133], v[178:181], v[62:65]
	v_mfma_f32_16x16x32_bf16 v[62:65], v[134:137], v[190:193], v[62:65]
	v_mfma_f32_16x16x32_bf16 v[58:61], v[138:141], v[178:181], v[58:61]
	v_mfma_f32_16x16x32_bf16 v[58:61], v[142:145], v[190:193], v[58:61]
	v_mfma_f32_16x16x32_bf16 v[46:49], v[130:133], v[194:197], v[46:49]
	v_mfma_f32_16x16x32_bf16 v[46:49], v[134:137], v[198:201], v[46:49]
	v_mfma_f32_16x16x32_bf16 v[42:45], v[138:141], v[194:197], v[42:45]
	v_mfma_f32_16x16x32_bf16 v[42:45], v[142:145], v[198:201], v[42:45]
	v_mfma_f32_16x16x32_bf16 v[30:33], v[130:133], v[202:205], v[30:33]
	v_mfma_f32_16x16x32_bf16 v[30:33], v[134:137], v[206:209], v[30:33]
	v_mfma_f32_16x16x32_bf16 v[26:29], v[138:141], v[202:205], v[26:29]
	v_mfma_f32_16x16x32_bf16 v[26:29], v[142:145], v[206:209], v[26:29]
	v_mfma_f32_16x16x32_bf16 v[14:17], v[130:133], v[210:213], v[14:17]
	v_mfma_f32_16x16x32_bf16 v[14:17], v[134:137], v[214:217], v[14:17]
	v_mfma_f32_16x16x32_bf16 v[10:13], v[138:141], v[210:213], v[10:13]
	v_mfma_f32_16x16x32_bf16 v[10:13], v[142:145], v[214:217], v[10:13]
	s_setprio 0
	s_setprio 1
	v_mfma_f32_16x16x32_bf16 v[54:57], v[146:149], v[178:181], v[54:57]
	v_mfma_f32_16x16x32_bf16 v[54:57], v[150:153], v[190:193], v[54:57]
	v_mfma_f32_16x16x32_bf16 v[50:53], v[170:173], v[178:181], v[50:53]
	v_mfma_f32_16x16x32_bf16 v[50:53], v[174:177], v[190:193], v[50:53]
	v_mfma_f32_16x16x32_bf16 v[38:41], v[146:149], v[194:197], v[38:41]
	v_mfma_f32_16x16x32_bf16 v[38:41], v[150:153], v[198:201], v[38:41]
	v_mfma_f32_16x16x32_bf16 v[34:37], v[170:173], v[194:197], v[34:37]
	v_mfma_f32_16x16x32_bf16 v[34:37], v[174:177], v[198:201], v[34:37]
	v_mfma_f32_16x16x32_bf16 v[22:25], v[146:149], v[202:205], v[22:25]
	v_mfma_f32_16x16x32_bf16 v[22:25], v[150:153], v[206:209], v[22:25]
	v_mfma_f32_16x16x32_bf16 v[18:21], v[170:173], v[202:205], v[18:21]
	v_mfma_f32_16x16x32_bf16 v[18:21], v[174:177], v[206:209], v[18:21]
	v_mfma_f32_16x16x32_bf16 v[6:9], v[146:149], v[210:213], v[6:9]
	v_mfma_f32_16x16x32_bf16 v[6:9], v[150:153], v[214:217], v[6:9]
	v_mfma_f32_16x16x32_bf16 v[2:5], v[170:173], v[210:213], v[2:5]
	v_mfma_f32_16x16x32_bf16 v[2:5], v[174:177], v[214:217], v[2:5]
	s_setprio 0
	s_barrier
	s_add_i32 s60, 0, 0x18000
	s_add_i32 s61, 0, 0x1c000
	v_add_u32_e32 v142, s60, v182
	v_add_u32_e32 v174, s61, v182
	ds_read_b128 v[130:133], v142
	ds_read_b128 v[134:137], v142 offset:1024
	ds_read_b128 v[138:141], v142 offset:2048
	ds_read_b128 v[142:145], v142 offset:3072
	ds_read_b128 v[146:149], v174
	ds_read_b128 v[150:153], v174 offset:1024
	ds_read_b128 v[170:173], v174 offset:2048
	ds_read_b128 v[174:177], v174 offset:3072
	s_add_u32 s0, s40, 0x80000
	s_addc_u32 s1, s41, 0
	s_mov_b32 m0, s47
	v_lshl_add_u64 v[226:227], s[0:1], 0, v[154:155]
	ds_read_b128 v[178:181], v188 offset:32768
	ds_read_b128 v[190:193], v188 offset:33792
	ds_read_b128 v[194:197], v188 offset:34816
	ds_read_b128 v[198:201], v188 offset:35840
	ds_read_b128 v[202:205], v188 offset:36864
	ds_read_b128 v[206:209], v188 offset:37888
	ds_read_b128 v[210:213], v188 offset:38912
	ds_read_b128 v[214:217], v188 offset:39936
	global_load_lds_dwordx4 v[226:227], off
	v_lshl_add_u64 v[226:227], s[0:1], 0, v[158:159]
	s_mov_b32 m0, s48
	s_nop 0
	global_load_lds_dwordx4 v[226:227], off
	s_waitcnt vmcnt(8)
	s_waitcnt lgkmcnt(0)
	s_barrier
	s_setprio 1
	s_waitcnt lgkmcnt(0)
	v_mfma_f32_16x16x32_bf16 v[126:129], v[130:133], v[178:181], v[126:129]
	v_mfma_f32_16x16x32_bf16 v[126:129], v[134:137], v[190:193], v[126:129]
	v_mfma_f32_16x16x32_bf16 v[122:125], v[138:141], v[178:181], v[122:125]
	v_mfma_f32_16x16x32_bf16 v[122:125], v[142:145], v[190:193], v[122:125]
	v_mfma_f32_16x16x32_bf16 v[110:113], v[130:133], v[194:197], v[110:113]
	v_mfma_f32_16x16x32_bf16 v[110:113], v[134:137], v[198:201], v[110:113]
	v_mfma_f32_16x16x32_bf16 v[106:109], v[138:141], v[194:197], v[106:109]
	v_mfma_f32_16x16x32_bf16 v[106:109], v[142:145], v[198:201], v[106:109]
	v_mfma_f32_16x16x32_bf16 v[94:97], v[130:133], v[202:205], v[94:97]
	v_mfma_f32_16x16x32_bf16 v[94:97], v[134:137], v[206:209], v[94:97]
	v_mfma_f32_16x16x32_bf16 v[90:93], v[138:141], v[202:205], v[90:93]
	v_mfma_f32_16x16x32_bf16 v[90:93], v[142:145], v[206:209], v[90:93]
	v_mfma_f32_16x16x32_bf16 v[78:81], v[130:133], v[210:213], v[78:81]
	v_mfma_f32_16x16x32_bf16 v[78:81], v[134:137], v[214:217], v[78:81]
	v_mfma_f32_16x16x32_bf16 v[74:77], v[138:141], v[210:213], v[74:77]
	v_mfma_f32_16x16x32_bf16 v[74:77], v[142:145], v[214:217], v[74:77]
	s_setprio 0
	s_setprio 1
	v_mfma_f32_16x16x32_bf16 v[118:121], v[146:149], v[178:181], v[118:121]
	v_mfma_f32_16x16x32_bf16 v[118:121], v[150:153], v[190:193], v[118:121]
	v_mfma_f32_16x16x32_bf16 v[114:117], v[170:173], v[178:181], v[114:117]
	v_mfma_f32_16x16x32_bf16 v[114:117], v[174:177], v[190:193], v[114:117]
	v_mfma_f32_16x16x32_bf16 v[102:105], v[146:149], v[194:197], v[102:105]
	v_mfma_f32_16x16x32_bf16 v[102:105], v[150:153], v[198:201], v[102:105]
	v_mfma_f32_16x16x32_bf16 v[98:101], v[170:173], v[194:197], v[98:101]
	v_mfma_f32_16x16x32_bf16 v[98:101], v[174:177], v[198:201], v[98:101]
	v_mfma_f32_16x16x32_bf16 v[86:89], v[146:149], v[202:205], v[86:89]
	v_mfma_f32_16x16x32_bf16 v[86:89], v[150:153], v[206:209], v[86:89]
	v_mfma_f32_16x16x32_bf16 v[82:85], v[170:173], v[202:205], v[82:85]
	v_mfma_f32_16x16x32_bf16 v[82:85], v[174:177], v[206:209], v[82:85]
	v_mfma_f32_16x16x32_bf16 v[70:73], v[146:149], v[210:213], v[70:73]
	v_mfma_f32_16x16x32_bf16 v[70:73], v[150:153], v[214:217], v[70:73]
	v_mfma_f32_16x16x32_bf16 v[66:69], v[170:173], v[210:213], v[66:69]
	v_mfma_f32_16x16x32_bf16 v[66:69], v[174:177], v[214:217], v[66:69]
	s_setprio 0
	s_barrier
	s_add_i32 s0, s60, s45
	v_lshl_add_u64 v[218:219], v[218:219], 0, s[14:15]
	s_mov_b32 m0, s0
	ds_read_b128 v[178:181], v188 offset:49152
	ds_read_b128 v[190:193], v188 offset:50176
	ds_read_b128 v[194:197], v188 offset:51200
	ds_read_b128 v[198:201], v188 offset:52224
	ds_read_b128 v[202:205], v188 offset:53248
	ds_read_b128 v[206:209], v188 offset:54272
	ds_read_b128 v[210:213], v188 offset:55296
	ds_read_b128 v[214:217], v188 offset:56320
	global_load_lds_dwordx4 v[218:219], off
	s_add_i32 m0, s0, 0x2000
	s_add_u32 s0, s2, 0x80080
	v_lshl_add_u64 v[218:219], v[220:221], 0, s[14:15]
	s_addc_u32 s1, s3, 0
	s_add_i32 s2, s61, s45
	global_load_lds_dwordx4 v[218:219], off
	v_lshl_add_u64 v[218:219], s[0:1], 0, v[156:157]
	s_mov_b32 m0, s2
	s_nop 0
	global_load_lds_dwordx4 v[218:219], off
	v_lshl_add_u64 v[218:219], s[0:1], 0, v[160:161]
	s_add_i32 m0, s2, 0x2000
	s_nop 0
	global_load_lds_dwordx4 v[218:219], off
	v_lshl_add_u64 v[218:219], v[222:223], 0, s[14:15]
	s_mov_b32 m0, s50
	s_nop 0
	global_load_lds_dwordx4 v[218:219], off
	v_lshl_add_u64 v[218:219], v[224:225], 0, s[14:15]
	s_mov_b32 m0, s51
	s_nop 0
	global_load_lds_dwordx4 v[218:219], off
	s_waitcnt vmcnt(8)
	s_waitcnt lgkmcnt(0)
	s_barrier
	s_setprio 1
	s_waitcnt lgkmcnt(0)
	v_mfma_f32_16x16x32_bf16 v[62:65], v[130:133], v[178:181], v[62:65]
	v_mfma_f32_16x16x32_bf16 v[62:65], v[134:137], v[190:193], v[62:65]
	v_mfma_f32_16x16x32_bf16 v[58:61], v[138:141], v[178:181], v[58:61]
	v_mfma_f32_16x16x32_bf16 v[58:61], v[142:145], v[190:193], v[58:61]
	v_mfma_f32_16x16x32_bf16 v[46:49], v[130:133], v[194:197], v[46:49]
	v_mfma_f32_16x16x32_bf16 v[46:49], v[134:137], v[198:201], v[46:49]
	v_mfma_f32_16x16x32_bf16 v[42:45], v[138:141], v[194:197], v[42:45]
	v_mfma_f32_16x16x32_bf16 v[42:45], v[142:145], v[198:201], v[42:45]
	v_mfma_f32_16x16x32_bf16 v[30:33], v[130:133], v[202:205], v[30:33]
	v_mfma_f32_16x16x32_bf16 v[30:33], v[134:137], v[206:209], v[30:33]
	v_mfma_f32_16x16x32_bf16 v[26:29], v[138:141], v[202:205], v[26:29]
	v_mfma_f32_16x16x32_bf16 v[26:29], v[142:145], v[206:209], v[26:29]
	v_mfma_f32_16x16x32_bf16 v[14:17], v[130:133], v[210:213], v[14:17]
	v_mfma_f32_16x16x32_bf16 v[14:17], v[134:137], v[214:217], v[14:17]
	v_mfma_f32_16x16x32_bf16 v[10:13], v[138:141], v[210:213], v[10:13]
	v_mfma_f32_16x16x32_bf16 v[10:13], v[142:145], v[214:217], v[10:13]
	s_setprio 0
	s_setprio 1
	v_mfma_f32_16x16x32_bf16 v[54:57], v[146:149], v[178:181], v[54:57]
	v_mfma_f32_16x16x32_bf16 v[54:57], v[150:153], v[190:193], v[54:57]
	v_mfma_f32_16x16x32_bf16 v[50:53], v[170:173], v[178:181], v[50:53]
	v_mfma_f32_16x16x32_bf16 v[50:53], v[174:177], v[190:193], v[50:53]
	v_mfma_f32_16x16x32_bf16 v[38:41], v[146:149], v[194:197], v[38:41]
	v_mfma_f32_16x16x32_bf16 v[38:41], v[150:153], v[198:201], v[38:41]
	v_mfma_f32_16x16x32_bf16 v[34:37], v[170:173], v[194:197], v[34:37]
	v_mfma_f32_16x16x32_bf16 v[34:37], v[174:177], v[198:201], v[34:37]
	v_mfma_f32_16x16x32_bf16 v[22:25], v[146:149], v[202:205], v[22:25]
	v_mfma_f32_16x16x32_bf16 v[22:25], v[150:153], v[206:209], v[22:25]
	v_mfma_f32_16x16x32_bf16 v[18:21], v[170:173], v[202:205], v[18:21]
	v_mfma_f32_16x16x32_bf16 v[18:21], v[174:177], v[206:209], v[18:21]
	v_mfma_f32_16x16x32_bf16 v[6:9], v[146:149], v[210:213], v[6:9]
	v_mfma_f32_16x16x32_bf16 v[6:9], v[150:153], v[214:217], v[6:9]
	v_mfma_f32_16x16x32_bf16 v[2:5], v[170:173], v[210:213], v[2:5]
	v_mfma_f32_16x16x32_bf16 v[2:5], v[174:177], v[214:217], v[2:5]
	s_setprio 0
	s_barrier
	s_add_i32 s59, s59, 2
	s_add_u32 s38, s38, 0x100
	s_addc_u32 s39, s39, 0
	s_add_u32 s57, s57, 0x100
	s_addc_u32 s58, s58, 0
	s_cmp_gt_u32 s59, 29
	s_cbranch_scc0 .LBB0_1626
	s_and_b64 vcc, exec, s[16:17]
	s_cbranch_vccz .LBB0_1629
	s_barrier

.LBB0_1830:
	v_lshl_add_u32 v238, s13, 8, v1
	v_lshlrev_b32_e32 v238, 11, v238
	v_mov_b32_e32 v239, 0
	v_lshl_or_b32 v240, s12, 8, v183
	v_lshlrev_b32_e32 v240, 1, v240
	v_mov_b32_e32 v241, 0
	v_lshl_add_u64 v[240:241], s[78:79], 0, v[240:241]
	v_lshl_add_u64 v[238:239], v[240:241], 0, v[238:239]
	v_mov_b32_e32 v242, 0x8000
	v_mov_b32_e32 v243, 0
	global_load_dwordx4 v[246:249], v[238:239], off
	global_load_dwordx4 v[246:249], v[238:239], off offset:256
	v_lshl_add_u64 v[238:239], v[238:239], 0, v[242:243]
	global_load_dwordx4 v[246:249], v[238:239], off
	global_load_dwordx4 v[246:249], v[238:239], off offset:256
	v_lshl_add_u64 v[238:239], v[238:239], 0, v[242:243]
	global_load_dwordx4 v[246:249], v[238:239], off
	global_load_dwordx4 v[246:249], v[238:239], off offset:256
	v_lshl_add_u64 v[238:239], v[238:239], 0, v[242:243]
	global_load_dwordx4 v[246:249], v[238:239], off
	global_load_dwordx4 v[246:249], v[238:239], off offset:256
	s_add_i32 s44, s44, 1
	s_mul_i32 s0, s44, s47
	s_mul_hi_u32 s1, s44, s75
	s_add_i32 s1, s1, s0
	s_mul_i32 s0, s44, s75
	s_add_u32 s6, s0, s64
	s_addc_u32 s7, s1, s48
	v_cmp_gt_i64_e32 vcc, s[6:7], v[168:169]
	v_cmp_lt_i64_e64 s[8:9], s[6:7], v[166:167]
	s_cbranch_vccnz .LBB0_1836
	s_ashr_i32 s0, s6, 31
	s_lshr_b32 s0, s0, 29
	s_add_i32 s0, s6, s0
	s_and_b32 s1, s0, -8
	s_sub_i32 s1, s6, s1
	s_cmp_gt_i32 s1, -1
	s_mov_b64 s[6:7], -1
	s_cbranch_scc0 .LBB0_1833
	s_lshl_b32 s28, s1, 5
	s_mov_b64 s[6:7], 0

.LBB0_1840:
	s_add_u32 s30, s30, 0xb0080
	s_addc_u32 s31, s31, 0
	s_add_u32 s53, s2, 0x100
	v_mov_b32_e32 v2, 0
	s_addc_u32 s54, s3, 0
	s_mov_b32 s55, -2
	s_waitcnt lgkmcnt(0)
	v_mov_b32_e32 v3, v2
	v_mov_b32_e32 v4, v2
	v_mov_b32_e32 v5, v2
	v_mov_b32_e32 v6, v2
	v_mov_b32_e32 v7, v2
	v_mov_b32_e32 v8, v2
	v_mov_b32_e32 v9, v2
	v_mov_b32_e32 v18, v2
	v_mov_b32_e32 v19, v2
	v_mov_b32_e32 v20, v2
	v_mov_b32_e32 v21, v2
	v_mov_b32_e32 v22, v2
	v_mov_b32_e32 v23, v2
	v_mov_b32_e32 v24, v2
	v_mov_b32_e32 v25, v2
	v_mov_b32_e32 v34, v2
	v_mov_b32_e32 v35, v2
	v_mov_b32_e32 v36, v2
	v_mov_b32_e32 v37, v2
	v_mov_b32_e32 v38, v2
	v_mov_b32_e32 v39, v2
	v_mov_b32_e32 v40, v2
	v_mov_b32_e32 v41, v2
	v_mov_b32_e32 v50, v2
	v_mov_b32_e32 v51, v2
	v_mov_b32_e32 v52, v2
	v_mov_b32_e32 v53, v2
	v_mov_b32_e32 v54, v2
	v_mov_b32_e32 v55, v2
	v_mov_b32_e32 v56, v2
	v_mov_b32_e32 v57, v2
	v_mov_b32_e32 v10, v2
	v_mov_b32_e32 v11, v2
	v_mov_b32_e32 v12, v2
	v_mov_b32_e32 v13, v2
	v_mov_b32_e32 v14, v2
	v_mov_b32_e32 v15, v2
	v_mov_b32_e32 v16, v2
	v_mov_b32_e32 v17, v2
	v_mov_b32_e32 v26, v2
	v_mov_b32_e32 v27, v2
	v_mov_b32_e32 v28, v2
	v_mov_b32_e32 v29, v2
	v_mov_b32_e32 v30, v2
	v_mov_b32_e32 v31, v2
	v_mov_b32_e32 v32, v2
	v_mov_b32_e32 v33, v2
	v_mov_b32_e32 v42, v2
	v_mov_b32_e32 v43, v2
	v_mov_b32_e32 v44, v2
	v_mov_b32_e32 v45, v2
	v_mov_b32_e32 v46, v2
	v_mov_b32_e32 v47, v2
	v_mov_b32_e32 v48, v2
	v_mov_b32_e32 v49, v2
	v_mov_b32_e32 v58, v2
	v_mov_b32_e32 v59, v2
	v_mov_b32_e32 v60, v2
	v_mov_b32_e32 v61, v2
	v_mov_b32_e32 v62, v2
	v_mov_b32_e32 v63, v2
	v_mov_b32_e32 v64, v2
	v_mov_b32_e32 v65, v2
	v_mov_b32_e32 v66, v2
	v_mov_b32_e32 v67, v2
	v_mov_b32_e32 v68, v2
	v_mov_b32_e32 v69, v2
	v_mov_b32_e32 v70, v2
	v_mov_b32_e32 v71, v2
	v_mov_b32_e32 v72, v2
	v_mov_b32_e32 v73, v2
	v_mov_b32_e32 v82, v2
	v_mov_b32_e32 v83, v2
	v_mov_b32_e32 v84, v2
	v_mov_b32_e32 v85, v2
	v_mov_b32_e32 v86, v2
	v_mov_b32_e32 v87, v2
	v_mov_b32_e32 v88, v2
	v_mov_b32_e32 v89, v2
	v_mov_b32_e32 v98, v2
	v_mov_b32_e32 v99, v2
	v_mov_b32_e32 v100, v2
	v_mov_b32_e32 v101, v2
	v_mov_b32_e32 v102, v2
	v_mov_b32_e32 v103, v2
	v_mov_b32_e32 v104, v2
	v_mov_b32_e32 v105, v2
	v_mov_b32_e32 v114, v2
	v_mov_b32_e32 v115, v2
	v_mov_b32_e32 v116, v2
	v_mov_b32_e32 v117, v2
	v_mov_b32_e32 v118, v2
	v_mov_b32_e32 v119, v2
	v_mov_b32_e32 v120, v2
	v_mov_b32_e32 v121, v2
	v_mov_b32_e32 v74, v2
	v_mov_b32_e32 v75, v2
	v_mov_b32_e32 v76, v2
	v_mov_b32_e32 v77, v2
	v_mov_b32_e32 v78, v2
	v_mov_b32_e32 v79, v2
	v_mov_b32_e32 v80, v2
	v_mov_b32_e32 v81, v2
	v_mov_b32_e32 v90, v2
	v_mov_b32_e32 v91, v2
	v_mov_b32_e32 v92, v2
	v_mov_b32_e32 v93, v2
	v_mov_b32_e32 v94, v2
	v_mov_b32_e32 v95, v2
	v_mov_b32_e32 v96, v2
	v_mov_b32_e32 v97, v2
	v_mov_b32_e32 v106, v2
	v_mov_b32_e32 v107, v2
	v_mov_b32_e32 v108, v2
	v_mov_b32_e32 v109, v2
	v_mov_b32_e32 v110, v2
	v_mov_b32_e32 v111, v2
	v_mov_b32_e32 v112, v2
	v_mov_b32_e32 v113, v2
	v_mov_b32_e32 v122, v2
	v_mov_b32_e32 v123, v2
	v_mov_b32_e32 v124, v2
	v_mov_b32_e32 v125, v2
	v_mov_b32_e32 v126, v2
	v_mov_b32_e32 v127, v2
	v_mov_b32_e32 v128, v2
	v_mov_b32_e32 v129, v2
	s_nop 0
	s_nop 0
	s_nop 0
	s_nop 0
	s_nop 0
	s_nop 0
	s_nop 0
	s_nop 0
	s_nop 0
	s_nop 0
	s_nop 0
	s_nop 0

.LBB0_2117:
	s_ashr_i32 s29, s28, 31
	s_lshl_b64 s[0:1], s[28:29], 19
	s_add_u32 s30, s33, s0
	s_addc_u32 s31, s42, s1
	s_and_b64 s[0:1], s[6:7], exec
	s_cselect_b32 s11, s31, s39
	s_cselect_b32 s29, s30, s38
	s_ashr_i32 s27, s26, 31
	s_lshl_b64 s[0:1], s[26:27], 19
	s_add_u32 s34, s43, s0
	s_addc_u32 s35, s44, s1
	s_and_b64 s[0:1], s[6:7], exec
	s_cselect_b32 s27, s35, s3
	s_cselect_b32 s56, s34, s2
	s_add_u32 s38, s38, 0x40080
	s_addc_u32 s39, s39, 0
	s_add_u32 s57, s2, 0x100
	v_mov_b32_e32 v2, 0
	s_addc_u32 s58, s3, 0
	s_mov_b32 s59, -2
	s_waitcnt lgkmcnt(0)
	v_mov_b32_e32 v3, v2
	v_mov_b32_e32 v4, v2
	v_mov_b32_e32 v5, v2
	v_mov_b32_e32 v6, v2
	v_mov_b32_e32 v7, v2
	v_mov_b32_e32 v8, v2
	v_mov_b32_e32 v9, v2
	v_mov_b32_e32 v18, v2
	v_mov_b32_e32 v19, v2
	v_mov_b32_e32 v20, v2
	v_mov_b32_e32 v21, v2
	v_mov_b32_e32 v22, v2
	v_mov_b32_e32 v23, v2
	v_mov_b32_e32 v24, v2
	v_mov_b32_e32 v25, v2
	v_mov_b32_e32 v34, v2
	v_mov_b32_e32 v35, v2
	v_mov_b32_e32 v36, v2
	v_mov_b32_e32 v37, v2
	v_mov_b32_e32 v38, v2
	v_mov_b32_e32 v39, v2
	v_mov_b32_e32 v40, v2
	v_mov_b32_e32 v41, v2
	v_mov_b32_e32 v50, v2
	v_mov_b32_e32 v51, v2
	v_mov_b32_e32 v52, v2
	v_mov_b32_e32 v53, v2
	v_mov_b32_e32 v54, v2
	v_mov_b32_e32 v55, v2
	v_mov_b32_e32 v56, v2
	v_mov_b32_e32 v57, v2
	v_mov_b32_e32 v10, v2
	v_mov_b32_e32 v11, v2
	v_mov_b32_e32 v12, v2
	v_mov_b32_e32 v13, v2
	v_mov_b32_e32 v14, v2
	v_mov_b32_e32 v15, v2
	v_mov_b32_e32 v16, v2
	v_mov_b32_e32 v17, v2
	v_mov_b32_e32 v26, v2
	v_mov_b32_e32 v27, v2
	v_mov_b32_e32 v28, v2
	v_mov_b32_e32 v29, v2
	v_mov_b32_e32 v30, v2
	v_mov_b32_e32 v31, v2
	v_mov_b32_e32 v32, v2
	v_mov_b32_e32 v33, v2
	v_mov_b32_e32 v42, v2
	v_mov_b32_e32 v43, v2
	v_mov_b32_e32 v44, v2
	v_mov_b32_e32 v45, v2
	v_mov_b32_e32 v46, v2
	v_mov_b32_e32 v47, v2
	v_mov_b32_e32 v48, v2
	v_mov_b32_e32 v49, v2
	v_mov_b32_e32 v58, v2
	v_mov_b32_e32 v59, v2
	v_mov_b32_e32 v60, v2
	v_mov_b32_e32 v61, v2
	v_mov_b32_e32 v62, v2
	v_mov_b32_e32 v63, v2
	v_mov_b32_e32 v64, v2
	v_mov_b32_e32 v65, v2
	v_mov_b32_e32 v66, v2
	v_mov_b32_e32 v67, v2
	v_mov_b32_e32 v68, v2
	v_mov_b32_e32 v69, v2
	v_mov_b32_e32 v70, v2
	v_mov_b32_e32 v71, v2
	v_mov_b32_e32 v72, v2
	v_mov_b32_e32 v73, v2
	v_mov_b32_e32 v82, v2
	v_mov_b32_e32 v83, v2
	v_mov_b32_e32 v84, v2
	v_mov_b32_e32 v85, v2
	v_mov_b32_e32 v86, v2
	v_mov_b32_e32 v87, v2
	v_mov_b32_e32 v88, v2
	v_mov_b32_e32 v89, v2
	v_mov_b32_e32 v98, v2
	v_mov_b32_e32 v99, v2
	v_mov_b32_e32 v100, v2
	v_mov_b32_e32 v101, v2
	v_mov_b32_e32 v102, v2
	v_mov_b32_e32 v103, v2
	v_mov_b32_e32 v104, v2
	v_mov_b32_e32 v105, v2
	v_mov_b32_e32 v114, v2
	v_mov_b32_e32 v115, v2
	v_mov_b32_e32 v116, v2
	v_mov_b32_e32 v117, v2
	v_mov_b32_e32 v118, v2
	v_mov_b32_e32 v119, v2
	v_mov_b32_e32 v120, v2
	v_mov_b32_e32 v121, v2
	v_mov_b32_e32 v74, v2
	v_mov_b32_e32 v75, v2
	v_mov_b32_e32 v76, v2
	v_mov_b32_e32 v77, v2
	v_mov_b32_e32 v78, v2
	v_mov_b32_e32 v79, v2
	v_mov_b32_e32 v80, v2
	v_mov_b32_e32 v81, v2
	v_mov_b32_e32 v90, v2
	v_mov_b32_e32 v91, v2
	v_mov_b32_e32 v92, v2
	v_mov_b32_e32 v93, v2
	v_mov_b32_e32 v94, v2
	v_mov_b32_e32 v95, v2
	v_mov_b32_e32 v96, v2
	v_mov_b32_e32 v97, v2
	v_mov_b32_e32 v106, v2
	v_mov_b32_e32 v107, v2
	v_mov_b32_e32 v108, v2
	v_mov_b32_e32 v109, v2
	v_mov_b32_e32 v110, v2
	v_mov_b32_e32 v111, v2
	v_mov_b32_e32 v112, v2
	v_mov_b32_e32 v113, v2
	v_mov_b32_e32 v122, v2
	v_mov_b32_e32 v123, v2
	v_mov_b32_e32 v124, v2
	v_mov_b32_e32 v125, v2
	v_mov_b32_e32 v126, v2
	v_mov_b32_e32 v127, v2
	v_mov_b32_e32 v128, v2
	v_mov_b32_e32 v129, v2
	s_nop 0
	s_nop 0
.LBB0_2118:
	ds_read_b128 v[130:133], v186
	ds_read_b128 v[134:137], v186 offset:1024
	ds_read_b128 v[138:141], v186 offset:2048
	ds_read_b128 v[142:145], v186 offset:3072
	ds_read_b128 v[146:149], v187
	ds_read_b128 v[150:153], v187 offset:1024
	ds_read_b128 v[170:173], v187 offset:2048
	ds_read_b128 v[174:177], v187 offset:3072
	s_add_u32 s0, s38, 0xfffc0080
	s_addc_u32 s1, s39, -1
	s_cmp_eq_u32 s59, 12
	s_cselect_b32 s41, s11, s1
	s_cselect_b32 s40, s29, s0
	s_cselect_b32 s3, s27, s58
	s_cselect_b32 s2, s56, s57
	v_lshl_add_u64 v[218:219], s[38:39], 0, v[162:163]
	s_add_i32 m0, s37, 0xc000
	ds_read_b128 v[178:181], v188
	ds_read_b128 v[190:193], v188 offset:1024
	ds_read_b128 v[194:197], v188 offset:2048
	ds_read_b128 v[198:201], v188 offset:3072
	ds_read_b128 v[202:205], v188 offset:4096
	ds_read_b128 v[206:209], v188 offset:5120
	ds_read_b128 v[210:213], v188 offset:6144
	ds_read_b128 v[214:217], v188 offset:7168
	global_load_lds_dwordx4 v[218:219], off
	v_lshl_add_u64 v[218:219], s[38:39], 0, v[164:165]
	s_add_i32 m0, s37, 0xe000
	s_nop 0
	global_load_lds_dwordx4 v[218:219], off
	s_waitcnt vmcnt(8)
	s_waitcnt lgkmcnt(0)
	s_barrier
	s_setprio 1
	s_waitcnt lgkmcnt(0)
	v_mfma_f32_16x16x32_bf16 v[126:129], v[130:133], v[178:181], v[126:129]
	v_mfma_f32_16x16x32_bf16 v[126:129], v[134:137], v[190:193], v[126:129]
	v_mfma_f32_16x16x32_bf16 v[122:125], v[138:141], v[178:181], v[122:125]
	v_mfma_f32_16x16x32_bf16 v[122:125], v[142:145], v[190:193], v[122:125]
	v_mfma_f32_16x16x32_bf16 v[110:113], v[130:133], v[194:197], v[110:113]
	v_mfma_f32_16x16x32_bf16 v[110:113], v[134:137], v[198:201], v[110:113]
	v_mfma_f32_16x16x32_bf16 v[106:109], v[138:141], v[194:197], v[106:109]
	v_mfma_f32_16x16x32_bf16 v[106:109], v[142:145], v[198:201], v[106:109]
	v_mfma_f32_16x16x32_bf16 v[94:97], v[130:133], v[202:205], v[94:97]
	v_mfma_f32_16x16x32_bf16 v[94:97], v[134:137], v[206:209], v[94:97]
	v_mfma_f32_16x16x32_bf16 v[90:93], v[138:141], v[202:205], v[90:93]
	v_mfma_f32_16x16x32_bf16 v[90:93], v[142:145], v[206:209], v[90:93]
	v_mfma_f32_16x16x32_bf16 v[78:81], v[130:133], v[210:213], v[78:81]
	v_mfma_f32_16x16x32_bf16 v[78:81], v[134:137], v[214:217], v[78:81]
	v_mfma_f32_16x16x32_bf16 v[74:77], v[138:141], v[210:213], v[74:77]
	v_mfma_f32_16x16x32_bf16 v[74:77], v[142:145], v[214:217], v[74:77]
	s_setprio 0
	s_setprio 1
	v_mfma_f32_16x16x32_bf16 v[118:121], v[146:149], v[178:181], v[118:121]
	v_mfma_f32_16x16x32_bf16 v[118:121], v[150:153], v[190:193], v[118:121]
	v_mfma_f32_16x16x32_bf16 v[114:117], v[170:173], v[178:181], v[114:117]
	v_mfma_f32_16x16x32_bf16 v[114:117], v[174:177], v[190:193], v[114:117]
	v_mfma_f32_16x16x32_bf16 v[102:105], v[146:149], v[194:197], v[102:105]
	v_mfma_f32_16x16x32_bf16 v[102:105], v[150:153], v[198:201], v[102:105]
	v_mfma_f32_16x16x32_bf16 v[98:101], v[170:173], v[194:197], v[98:101]
	v_mfma_f32_16x16x32_bf16 v[98:101], v[174:177], v[198:201], v[98:101]
	v_mfma_f32_16x16x32_bf16 v[86:89], v[146:149], v[202:205], v[86:89]
	v_mfma_f32_16x16x32_bf16 v[86:89], v[150:153], v[206:209], v[86:89]
	v_mfma_f32_16x16x32_bf16 v[82:85], v[170:173], v[202:205], v[82:85]
	v_mfma_f32_16x16x32_bf16 v[82:85], v[174:177], v[206:209], v[82:85]
	v_mfma_f32_16x16x32_bf16 v[70:73], v[146:149], v[210:213], v[70:73]
	v_mfma_f32_16x16x32_bf16 v[70:73], v[150:153], v[214:217], v[70:73]
	v_mfma_f32_16x16x32_bf16 v[66:69], v[170:173], v[210:213], v[66:69]
	v_mfma_f32_16x16x32_bf16 v[66:69], v[174:177], v[214:217], v[66:69]
	s_setprio 0
	s_barrier
	s_add_i32 s0, s54, s45
	v_lshl_add_u64 v[218:219], s[2:3], 0, v[156:157]
	s_mov_b32 m0, s0
	ds_read_b128 v[178:181], v188 offset:16384
	ds_read_b128 v[190:193], v188 offset:17408
	ds_read_b128 v[194:197], v188 offset:18432
	ds_read_b128 v[198:201], v188 offset:19456
	ds_read_b128 v[202:205], v188 offset:20480
	ds_read_b128 v[206:209], v188 offset:21504
	ds_read_b128 v[210:213], v188 offset:22528
	ds_read_b128 v[214:217], v188 offset:23552
	global_load_lds_dwordx4 v[218:219], off
	s_add_i32 m0, s0, 0x2000
	s_add_u32 s0, s2, 0x40000
	v_lshl_add_u64 v[220:221], s[2:3], 0, v[160:161]
	s_addc_u32 s1, s3, 0
	s_add_i32 s60, s55, s45
	global_load_lds_dwordx4 v[220:221], off
	v_lshl_add_u64 v[222:223], s[0:1], 0, v[156:157]
	s_mov_b32 m0, s60
	v_lshl_add_u64 v[224:225], s[40:41], 0, v[158:159]
	global_load_lds_dwordx4 v[222:223], off
	v_lshl_add_u64 v[222:223], s[0:1], 0, v[160:161]
	s_add_i32 m0, s60, 0x2000
	s_nop 0
	global_load_lds_dwordx4 v[222:223], off
	v_lshl_add_u64 v[222:223], s[40:41], 0, v[154:155]
	s_mov_b32 m0, s37
	s_nop 0
	global_load_lds_dwordx4 v[222:223], off
	s_mov_b32 m0, s46
	s_nop 0
	global_load_lds_dwordx4 v[224:225], off
	s_waitcnt vmcnt(8)
	s_waitcnt lgkmcnt(0)
	s_barrier
	s_setprio 1
	s_waitcnt lgkmcnt(0)
	v_mfma_f32_16x16x32_bf16 v[62:65], v[130:133], v[178:181], v[62:65]
	v_mfma_f32_16x16x32_bf16 v[62:65], v[134:137], v[190:193], v[62:65]
	v_mfma_f32_16x16x32_bf16 v[58:61], v[138:141], v[178:181], v[58:61]
	v_mfma_f32_16x16x32_bf16 v[58:61], v[142:145], v[190:193], v[58:61]
	v_mfma_f32_16x16x32_bf16 v[46:49], v[130:133], v[194:197], v[46:49]
	v_mfma_f32_16x16x32_bf16 v[46:49], v[134:137], v[198:201], v[46:49]
	v_mfma_f32_16x16x32_bf16 v[42:45], v[138:141], v[194:197], v[42:45]
	v_mfma_f32_16x16x32_bf16 v[42:45], v[142:145], v[198:201], v[42:45]
	v_mfma_f32_16x16x32_bf16 v[30:33], v[130:133], v[202:205], v[30:33]
	v_mfma_f32_16x16x32_bf16 v[30:33], v[134:137], v[206:209], v[30:33]
	v_mfma_f32_16x16x32_bf16 v[26:29], v[138:141], v[202:205], v[26:29]
	v_mfma_f32_16x16x32_bf16 v[26:29], v[142:145], v[206:209], v[26:29]
	v_mfma_f32_16x16x32_bf16 v[14:17], v[130:133], v[210:213], v[14:17]
	v_mfma_f32_16x16x32_bf16 v[14:17], v[134:137], v[214:217], v[14:17]
	v_mfma_f32_16x16x32_bf16 v[10:13], v[138:141], v[210:213], v[10:13]
	v_mfma_f32_16x16x32_bf16 v[10:13], v[142:145], v[214:217], v[10:13]
	s_setprio 0
	s_setprio 1
	v_mfma_f32_16x16x32_bf16 v[54:57], v[146:149], v[178:181], v[54:57]
	v_mfma_f32_16x16x32_bf16 v[54:57], v[150:153], v[190:193], v[54:57]
	v_mfma_f32_16x16x32_bf16 v[50:53], v[170:173], v[178:181], v[50:53]
	v_mfma_f32_16x16x32_bf16 v[50:53], v[174:177], v[190:193], v[50:53]
	v_mfma_f32_16x16x32_bf16 v[38:41], v[146:149], v[194:197], v[38:41]
	v_mfma_f32_16x16x32_bf16 v[38:41], v[150:153], v[198:201], v[38:41]
	v_mfma_f32_16x16x32_bf16 v[34:37], v[170:173], v[194:197], v[34:37]
	v_mfma_f32_16x16x32_bf16 v[34:37], v[174:177], v[198:201], v[34:37]
	v_mfma_f32_16x16x32_bf16 v[22:25], v[146:149], v[202:205], v[22:25]
	v_mfma_f32_16x16x32_bf16 v[22:25], v[150:153], v[206:209], v[22:25]
	v_mfma_f32_16x16x32_bf16 v[18:21], v[170:173], v[202:205], v[18:21]
	v_mfma_f32_16x16x32_bf16 v[18:21], v[174:177], v[206:209], v[18:21]
	v_mfma_f32_16x16x32_bf16 v[6:9], v[146:149], v[210:213], v[6:9]
	v_mfma_f32_16x16x32_bf16 v[6:9], v[150:153], v[214:217], v[6:9]
	v_mfma_f32_16x16x32_bf16 v[2:5], v[170:173], v[210:213], v[2:5]
	v_mfma_f32_16x16x32_bf16 v[2:5], v[174:177], v[214:217], v[2:5]
	s_setprio 0
	s_barrier
	s_add_i32 s60, 0, 0x18000
	s_add_i32 s61, 0, 0x1c000
	v_add_u32_e32 v142, s60, v182
	v_add_u32_e32 v174, s61, v182
	ds_read_b128 v[130:133], v142
	ds_read_b128 v[134:137], v142 offset:1024
	ds_read_b128 v[138:141], v142 offset:2048
	ds_read_b128 v[142:145], v142 offset:3072
	ds_read_b128 v[146:149], v174
	ds_read_b128 v[150:153], v174 offset:1024
	ds_read_b128 v[170:173], v174 offset:2048
	ds_read_b128 v[174:177], v174 offset:3072
	s_add_u32 s0, s40, 0x40000
	s_addc_u32 s1, s41, 0
	s_mov_b32 m0, s47
	v_lshl_add_u64 v[226:227], s[0:1], 0, v[154:155]
	ds_read_b128 v[178:181], v188 offset:32768
	ds_read_b128 v[190:193], v188 offset:33792
	ds_read_b128 v[194:197], v188 offset:34816
	ds_read_b128 v[198:201], v188 offset:35840
	ds_read_b128 v[202:205], v188 offset:36864
	ds_read_b128 v[206:209], v188 offset:37888
	ds_read_b128 v[210:213], v188 offset:38912
	ds_read_b128 v[214:217], v188 offset:39936
	global_load_lds_dwordx4 v[226:227], off
	v_lshl_add_u64 v[226:227], s[0:1], 0, v[158:159]
	s_mov_b32 m0, s48
	s_nop 0
	global_load_lds_dwordx4 v[226:227], off
	s_waitcnt vmcnt(8)
	s_waitcnt lgkmcnt(0)
	s_barrier
	s_setprio 1
	s_waitcnt lgkmcnt(0)
	v_mfma_f32_16x16x32_bf16 v[126:129], v[130:133], v[178:181], v[126:129]
	v_mfma_f32_16x16x32_bf16 v[126:129], v[134:137], v[190:193], v[126:129]
	v_mfma_f32_16x16x32_bf16 v[122:125], v[138:141], v[178:181], v[122:125]
	v_mfma_f32_16x16x32_bf16 v[122:125], v[142:145], v[190:193], v[122:125]
	v_mfma_f32_16x16x32_bf16 v[110:113], v[130:133], v[194:197], v[110:113]
	v_mfma_f32_16x16x32_bf16 v[110:113], v[134:137], v[198:201], v[110:113]
	v_mfma_f32_16x16x32_bf16 v[106:109], v[138:141], v[194:197], v[106:109]
	v_mfma_f32_16x16x32_bf16 v[106:109], v[142:145], v[198:201], v[106:109]
	v_mfma_f32_16x16x32_bf16 v[94:97], v[130:133], v[202:205], v[94:97]
	v_mfma_f32_16x16x32_bf16 v[94:97], v[134:137], v[206:209], v[94:97]
	v_mfma_f32_16x16x32_bf16 v[90:93], v[138:141], v[202:205], v[90:93]
	v_mfma_f32_16x16x32_bf16 v[90:93], v[142:145], v[206:209], v[90:93]
	v_mfma_f32_16x16x32_bf16 v[78:81], v[130:133], v[210:213], v[78:81]
	v_mfma_f32_16x16x32_bf16 v[78:81], v[134:137], v[214:217], v[78:81]
	v_mfma_f32_16x16x32_bf16 v[74:77], v[138:141], v[210:213], v[74:77]
	v_mfma_f32_16x16x32_bf16 v[74:77], v[142:145], v[214:217], v[74:77]
	s_setprio 0
	s_setprio 1
	v_mfma_f32_16x16x32_bf16 v[118:121], v[146:149], v[178:181], v[118:121]
	v_mfma_f32_16x16x32_bf16 v[118:121], v[150:153], v[190:193], v[118:121]
	v_mfma_f32_16x16x32_bf16 v[114:117], v[170:173], v[178:181], v[114:117]
	v_mfma_f32_16x16x32_bf16 v[114:117], v[174:177], v[190:193], v[114:117]
	v_mfma_f32_16x16x32_bf16 v[102:105], v[146:149], v[194:197], v[102:105]
	v_mfma_f32_16x16x32_bf16 v[102:105], v[150:153], v[198:201], v[102:105]
	v_mfma_f32_16x16x32_bf16 v[98:101], v[170:173], v[194:197], v[98:101]
	v_mfma_f32_16x16x32_bf16 v[98:101], v[174:177], v[198:201], v[98:101]
	v_mfma_f32_16x16x32_bf16 v[86:89], v[146:149], v[202:205], v[86:89]
	v_mfma_f32_16x16x32_bf16 v[86:89], v[150:153], v[206:209], v[86:89]
	v_mfma_f32_16x16x32_bf16 v[82:85], v[170:173], v[202:205], v[82:85]
	v_mfma_f32_16x16x32_bf16 v[82:85], v[174:177], v[206:209], v[82:85]
	v_mfma_f32_16x16x32_bf16 v[70:73], v[146:149], v[210:213], v[70:73]
	v_mfma_f32_16x16x32_bf16 v[70:73], v[150:153], v[214:217], v[70:73]
	v_mfma_f32_16x16x32_bf16 v[66:69], v[170:173], v[210:213], v[66:69]
	v_mfma_f32_16x16x32_bf16 v[66:69], v[174:177], v[214:217], v[66:69]
	s_setprio 0
	s_barrier
	s_add_i32 s0, s60, s45
	v_lshl_add_u64 v[218:219], v[218:219], 0, s[16:17]
	s_mov_b32 m0, s0
	ds_read_b128 v[178:181], v188 offset:49152
	ds_read_b128 v[190:193], v188 offset:50176
	ds_read_b128 v[194:197], v188 offset:51200
	ds_read_b128 v[198:201], v188 offset:52224
	ds_read_b128 v[202:205], v188 offset:53248
	ds_read_b128 v[206:209], v188 offset:54272
	ds_read_b128 v[210:213], v188 offset:55296
	ds_read_b128 v[214:217], v188 offset:56320
	global_load_lds_dwordx4 v[218:219], off
	s_add_i32 m0, s0, 0x2000
	s_add_u32 s0, s2, 0x40080
	v_lshl_add_u64 v[218:219], v[220:221], 0, s[16:17]
	s_addc_u32 s1, s3, 0
	s_add_i32 s2, s61, s45
	global_load_lds_dwordx4 v[218:219], off
	v_lshl_add_u64 v[218:219], s[0:1], 0, v[156:157]
	s_mov_b32 m0, s2
	s_nop 0
	global_load_lds_dwordx4 v[218:219], off
	v_lshl_add_u64 v[218:219], s[0:1], 0, v[160:161]
	s_add_i32 m0, s2, 0x2000
	s_nop 0
	global_load_lds_dwordx4 v[218:219], off
	v_lshl_add_u64 v[218:219], v[222:223], 0, s[16:17]
	s_mov_b32 m0, s50
	s_nop 0
	global_load_lds_dwordx4 v[218:219], off
	v_lshl_add_u64 v[218:219], v[224:225], 0, s[16:17]
	s_mov_b32 m0, s51
	s_nop 0
	global_load_lds_dwordx4 v[218:219], off
	s_waitcnt vmcnt(8)
	s_waitcnt lgkmcnt(0)
	s_barrier
	s_setprio 1
	s_waitcnt lgkmcnt(0)
	v_mfma_f32_16x16x32_bf16 v[62:65], v[130:133], v[178:181], v[62:65]
	v_mfma_f32_16x16x32_bf16 v[62:65], v[134:137], v[190:193], v[62:65]
	v_mfma_f32_16x16x32_bf16 v[58:61], v[138:141], v[178:181], v[58:61]
	v_mfma_f32_16x16x32_bf16 v[58:61], v[142:145], v[190:193], v[58:61]
	v_mfma_f32_16x16x32_bf16 v[46:49], v[130:133], v[194:197], v[46:49]
	v_mfma_f32_16x16x32_bf16 v[46:49], v[134:137], v[198:201], v[46:49]
	v_mfma_f32_16x16x32_bf16 v[42:45], v[138:141], v[194:197], v[42:45]
	v_mfma_f32_16x16x32_bf16 v[42:45], v[142:145], v[198:201], v[42:45]
	v_mfma_f32_16x16x32_bf16 v[30:33], v[130:133], v[202:205], v[30:33]
	v_mfma_f32_16x16x32_bf16 v[30:33], v[134:137], v[206:209], v[30:33]
	v_mfma_f32_16x16x32_bf16 v[26:29], v[138:141], v[202:205], v[26:29]
	v_mfma_f32_16x16x32_bf16 v[26:29], v[142:145], v[206:209], v[26:29]
	v_mfma_f32_16x16x32_bf16 v[14:17], v[130:133], v[210:213], v[14:17]
	v_mfma_f32_16x16x32_bf16 v[14:17], v[134:137], v[214:217], v[14:17]
	v_mfma_f32_16x16x32_bf16 v[10:13], v[138:141], v[210:213], v[10:13]
	v_mfma_f32_16x16x32_bf16 v[10:13], v[142:145], v[214:217], v[10:13]
	s_setprio 0
	s_setprio 1
	v_mfma_f32_16x16x32_bf16 v[54:57], v[146:149], v[178:181], v[54:57]
	v_mfma_f32_16x16x32_bf16 v[54:57], v[150:153], v[190:193], v[54:57]
	v_mfma_f32_16x16x32_bf16 v[50:53], v[170:173], v[178:181], v[50:53]
	v_mfma_f32_16x16x32_bf16 v[50:53], v[174:177], v[190:193], v[50:53]
	v_mfma_f32_16x16x32_bf16 v[38:41], v[146:149], v[194:197], v[38:41]
	v_mfma_f32_16x16x32_bf16 v[38:41], v[150:153], v[198:201], v[38:41]
	v_mfma_f32_16x16x32_bf16 v[34:37], v[170:173], v[194:197], v[34:37]
	v_mfma_f32_16x16x32_bf16 v[34:37], v[174:177], v[198:201], v[34:37]
	v_mfma_f32_16x16x32_bf16 v[22:25], v[146:149], v[202:205], v[22:25]
	v_mfma_f32_16x16x32_bf16 v[22:25], v[150:153], v[206:209], v[22:25]
	v_mfma_f32_16x16x32_bf16 v[18:21], v[170:173], v[202:205], v[18:21]
	v_mfma_f32_16x16x32_bf16 v[18:21], v[174:177], v[206:209], v[18:21]
	v_mfma_f32_16x16x32_bf16 v[6:9], v[146:149], v[210:213], v[6:9]
	v_mfma_f32_16x16x32_bf16 v[6:9], v[150:153], v[214:217], v[6:9]
	v_mfma_f32_16x16x32_bf16 v[2:5], v[170:173], v[210:213], v[2:5]
	v_mfma_f32_16x16x32_bf16 v[2:5], v[174:177], v[214:217], v[2:5]
	s_setprio 0
	s_barrier
	s_add_i32 s59, s59, 2
	s_add_u32 s38, s38, 0x100
	s_addc_u32 s39, s39, 0
	s_add_u32 s57, s57, 0x100
	s_addc_u32 s58, s58, 0
	s_cmp_gt_u32 s59, 13
	s_cbranch_scc0 .LBB0_2118
	s_and_b64 vcc, exec, s[18:19]
	s_cbranch_vccz .LBB0_2121
	s_barrier
